# K-loops: removed per-phase s_setprio toggles in all five GEMM mainloops (on top of SEC2/SEC4/SEC78 epilogue changes)
# speedup vs baseline: 1.0056x; 1.0056x over previous
.LBB0_54:
	s_add_u32 s4, s0, 0xfffc0080
	s_addc_u32 s5, s1, -1
	s_add_i32 s36, 0, 0x10000
	v_add_u32_e32 v2, s36, v243
	ds_read_b128 v[132:135], v2
	ds_read_b128 v[136:139], v2 offset:1024
	ds_read_b128 v[140:143], v2 offset:2048
	ds_read_b128 v[144:147], v2 offset:3072
	s_cmp_eq_u32 s21, 12
	s_cselect_b32 s17, s51, s5
	s_cselect_b32 s16, s50, s4
	s_cselect_b32 s5, s7, s20
	s_cselect_b32 s4, s6, s3
	v_lshl_add_u64 v[168:169], s[0:1], 0, v[184:185]
	s_add_i32 m0, s23, 0xc000
	ds_read_b128 v[148:151], v245
	ds_read_b128 v[152:155], v245 offset:1024
	ds_read_b128 v[156:159], v245 offset:2048
	ds_read_b128 v[160:163], v245 offset:3072
	ds_read_b128 v[188:191], v245 offset:4096
	ds_read_b128 v[192:195], v245 offset:5120
	ds_read_b128 v[196:199], v245 offset:6144
	ds_read_b128 v[200:203], v245 offset:7168
	global_load_lds_dwordx4 v[168:169], off
	v_lshl_add_u64 v[168:169], s[0:1], 0, v[186:187]
	s_add_i32 m0, s23, 0xe000
	s_nop 0
	global_load_lds_dwordx4 v[168:169], off
	s_waitcnt lgkmcnt(8)
	s_barrier
	s_waitcnt lgkmcnt(0)
	s_waitcnt lgkmcnt(0)
	v_mfma_f32_16x16x32_bf16 v[128:131], v[132:135], v[148:151], v[128:131]
	v_mfma_f32_16x16x32_bf16 v[124:127], v[140:143], v[148:151], v[124:127]
	v_mfma_f32_16x16x32_bf16 v[120:123], v[132:135], v[156:159], v[120:123]
	v_mfma_f32_16x16x32_bf16 v[116:119], v[140:143], v[156:159], v[116:119]
	v_mfma_f32_16x16x32_bf16 v[112:115], v[132:135], v[188:191], v[112:115]
	v_mfma_f32_16x16x32_bf16 v[108:111], v[140:143], v[188:191], v[108:111]
	v_mfma_f32_16x16x32_bf16 v[104:107], v[132:135], v[196:199], v[104:107]
	v_mfma_f32_16x16x32_bf16 v[100:103], v[140:143], v[196:199], v[100:103]
	v_mfma_f32_16x16x32_bf16 v[128:131], v[136:139], v[152:155], v[128:131]
	v_mfma_f32_16x16x32_bf16 v[124:127], v[144:147], v[152:155], v[124:127]
	v_mfma_f32_16x16x32_bf16 v[120:123], v[136:139], v[160:163], v[120:123]
	v_mfma_f32_16x16x32_bf16 v[116:119], v[144:147], v[160:163], v[116:119]
	v_mfma_f32_16x16x32_bf16 v[112:115], v[136:139], v[192:195], v[112:115]
	v_mfma_f32_16x16x32_bf16 v[108:111], v[144:147], v[192:195], v[108:111]
	v_mfma_f32_16x16x32_bf16 v[104:107], v[136:139], v[200:203], v[104:107]
	v_mfma_f32_16x16x32_bf16 v[100:103], v[144:147], v[200:203], v[100:103]
	s_barrier
	s_add_i32 s40, 0, 0x14000
	s_add_i32 s36, s36, s18
	v_add_u32_e32 v2, s40, v243
	v_lshl_add_u64 v[168:169], s[4:5], 0, v[172:173]
	s_mov_b32 m0, s36
	ds_read_b128 v[204:207], v2
	ds_read_b128 v[208:211], v2 offset:1024
	ds_read_b128 v[234:237], v2 offset:2048
	ds_read_b128 v[220:223], v2 offset:3072
	global_load_lds_dwordx4 v[168:169], off
	v_lshl_add_u64 v[238:239], s[4:5], 0, v[176:177]
	s_add_i32 m0, s36, 0x2000
	s_nop 0
	global_load_lds_dwordx4 v[238:239], off
	s_barrier
	s_waitcnt lgkmcnt(0)
	s_waitcnt lgkmcnt(0)
	v_mfma_f32_16x16x32_bf16 v[64:67], v[204:207], v[148:151], v[64:67]
	v_mfma_f32_16x16x32_bf16 v[60:63], v[234:237], v[148:151], v[60:63]
	v_mfma_f32_16x16x32_bf16 v[56:59], v[204:207], v[156:159], v[56:59]
	v_mfma_f32_16x16x32_bf16 v[52:55], v[234:237], v[156:159], v[52:55]
	v_mfma_f32_16x16x32_bf16 v[48:51], v[204:207], v[188:191], v[48:51]
	v_mfma_f32_16x16x32_bf16 v[44:47], v[234:237], v[188:191], v[44:47]
	v_mfma_f32_16x16x32_bf16 v[40:43], v[204:207], v[196:199], v[40:43]
	v_mfma_f32_16x16x32_bf16 v[36:39], v[234:237], v[196:199], v[36:39]
	v_mfma_f32_16x16x32_bf16 v[64:67], v[208:211], v[152:155], v[64:67]
	v_mfma_f32_16x16x32_bf16 v[60:63], v[220:223], v[152:155], v[60:63]
	v_mfma_f32_16x16x32_bf16 v[56:59], v[208:211], v[160:163], v[56:59]
	v_mfma_f32_16x16x32_bf16 v[52:55], v[220:223], v[160:163], v[52:55]
	v_mfma_f32_16x16x32_bf16 v[48:51], v[208:211], v[192:195], v[48:51]
	v_mfma_f32_16x16x32_bf16 v[44:47], v[220:223], v[192:195], v[44:47]
	v_mfma_f32_16x16x32_bf16 v[40:43], v[208:211], v[200:203], v[40:43]
	v_mfma_f32_16x16x32_bf16 v[36:39], v[220:223], v[200:203], v[36:39]
	s_mov_b32 m0, s23
	v_lshl_add_u64 v[214:215], s[16:17], 0, v[0:1]
	s_barrier
	ds_read_b128 v[148:151], v245 offset:16384
	ds_read_b128 v[152:155], v245 offset:17408
	ds_read_b128 v[156:159], v245 offset:18432
	ds_read_b128 v[160:163], v245 offset:19456
	ds_read_b128 v[188:191], v245 offset:20480
	ds_read_b128 v[192:195], v245 offset:21504
	ds_read_b128 v[196:199], v245 offset:22528
	ds_read_b128 v[200:203], v245 offset:23552
	global_load_lds_dwordx4 v[214:215], off
	v_lshl_add_u64 v[224:225], s[16:17], 0, v[174:175]
	s_mov_b32 m0, s26
	s_nop 0
	global_load_lds_dwordx4 v[224:225], off
	s_barrier
	s_waitcnt lgkmcnt(0)
	s_waitcnt lgkmcnt(0)
	v_mfma_f32_16x16x32_bf16 v[96:99], v[132:135], v[148:151], v[96:99]
	v_mfma_f32_16x16x32_bf16 v[92:95], v[140:143], v[148:151], v[92:95]
	v_mfma_f32_16x16x32_bf16 v[88:91], v[132:135], v[156:159], v[88:91]
	v_mfma_f32_16x16x32_bf16 v[84:87], v[140:143], v[156:159], v[84:87]
	v_mfma_f32_16x16x32_bf16 v[80:83], v[132:135], v[188:191], v[80:83]
	v_mfma_f32_16x16x32_bf16 v[76:79], v[140:143], v[188:191], v[76:79]
	v_mfma_f32_16x16x32_bf16 v[72:75], v[132:135], v[196:199], v[72:75]
	v_mfma_f32_16x16x32_bf16 v[68:71], v[140:143], v[196:199], v[68:71]
	v_mfma_f32_16x16x32_bf16 v[96:99], v[136:139], v[152:155], v[96:99]
	v_mfma_f32_16x16x32_bf16 v[92:95], v[144:147], v[152:155], v[92:95]
	v_mfma_f32_16x16x32_bf16 v[88:91], v[136:139], v[160:163], v[88:91]
	v_mfma_f32_16x16x32_bf16 v[84:87], v[144:147], v[160:163], v[84:87]
	v_mfma_f32_16x16x32_bf16 v[80:83], v[136:139], v[192:195], v[80:83]
	v_mfma_f32_16x16x32_bf16 v[76:79], v[144:147], v[192:195], v[76:79]
	v_mfma_f32_16x16x32_bf16 v[72:75], v[136:139], v[200:203], v[72:75]
	v_mfma_f32_16x16x32_bf16 v[68:71], v[144:147], v[200:203], v[68:71]
	s_barrier
	s_add_u32 s36, s4, 0x40000
	s_addc_u32 s37, s5, 0
	s_add_i32 s40, s40, s18
	v_lshl_add_u64 v[132:133], s[36:37], 0, v[172:173]
	s_mov_b32 m0, s40
	s_nop 0
	global_load_lds_dwordx4 v[132:133], off
	v_lshl_add_u64 v[132:133], s[36:37], 0, v[176:177]
	s_add_i32 m0, s40, 0x2000
	s_nop 0
	global_load_lds_dwordx4 v[132:133], off
	s_waitcnt vmcnt(6)
	s_barrier
	v_mfma_f32_16x16x32_bf16 v[32:35], v[204:207], v[148:151], v[32:35]
	v_mfma_f32_16x16x32_bf16 v[28:31], v[234:237], v[148:151], v[28:31]
	v_mfma_f32_16x16x32_bf16 v[24:27], v[204:207], v[156:159], v[24:27]
	v_mfma_f32_16x16x32_bf16 v[20:23], v[234:237], v[156:159], v[20:23]
	v_mfma_f32_16x16x32_bf16 v[16:19], v[204:207], v[188:191], v[16:19]
	v_mfma_f32_16x16x32_bf16 v[12:15], v[234:237], v[188:191], v[12:15]
	v_mfma_f32_16x16x32_bf16 v[8:11], v[204:207], v[196:199], v[8:11]
	v_mfma_f32_16x16x32_bf16 v[4:7], v[234:237], v[196:199], v[4:7]
	v_mfma_f32_16x16x32_bf16 v[32:35], v[208:211], v[152:155], v[32:35]
	v_mfma_f32_16x16x32_bf16 v[28:31], v[220:223], v[152:155], v[28:31]
	v_mfma_f32_16x16x32_bf16 v[24:27], v[208:211], v[160:163], v[24:27]
	v_mfma_f32_16x16x32_bf16 v[20:23], v[220:223], v[160:163], v[20:23]
	v_mfma_f32_16x16x32_bf16 v[16:19], v[208:211], v[192:195], v[16:19]
	v_mfma_f32_16x16x32_bf16 v[12:15], v[220:223], v[192:195], v[12:15]
	v_mfma_f32_16x16x32_bf16 v[8:11], v[208:211], v[200:203], v[8:11]
	v_mfma_f32_16x16x32_bf16 v[4:7], v[220:223], v[200:203], v[4:7]
	s_add_i32 s36, 0, 0x18000
	v_add_u32_e32 v2, s36, v243
	s_barrier
	ds_read_b128 v[132:135], v2
	ds_read_b128 v[136:139], v2 offset:1024
	ds_read_b128 v[140:143], v2 offset:2048
	ds_read_b128 v[144:147], v2 offset:3072
	s_add_u32 s16, s16, 0x40000
	s_addc_u32 s17, s17, 0
	s_mov_b32 m0, s27
	v_lshl_add_u64 v[204:205], s[16:17], 0, v[0:1]
	ds_read_b128 v[148:151], v245 offset:32768
	ds_read_b128 v[152:155], v245 offset:33792
	ds_read_b128 v[156:159], v245 offset:34816
	ds_read_b128 v[160:163], v245 offset:35840
	ds_read_b128 v[188:191], v245 offset:36864
	ds_read_b128 v[192:195], v245 offset:37888
	ds_read_b128 v[196:199], v245 offset:38912
	ds_read_b128 v[200:203], v245 offset:39936
	global_load_lds_dwordx4 v[204:205], off
	v_lshl_add_u64 v[204:205], s[16:17], 0, v[174:175]
	s_mov_b32 m0, s30
	s_nop 0
	global_load_lds_dwordx4 v[204:205], off
	s_waitcnt lgkmcnt(8)
	s_barrier
	s_waitcnt lgkmcnt(0)
	s_waitcnt lgkmcnt(0)
	v_mfma_f32_16x16x32_bf16 v[128:131], v[132:135], v[148:151], v[128:131]
	v_mfma_f32_16x16x32_bf16 v[124:127], v[140:143], v[148:151], v[124:127]
	v_mfma_f32_16x16x32_bf16 v[120:123], v[132:135], v[156:159], v[120:123]
	v_mfma_f32_16x16x32_bf16 v[116:119], v[140:143], v[156:159], v[116:119]
	v_mfma_f32_16x16x32_bf16 v[112:115], v[132:135], v[188:191], v[112:115]
	v_mfma_f32_16x16x32_bf16 v[108:111], v[140:143], v[188:191], v[108:111]
	v_mfma_f32_16x16x32_bf16 v[104:107], v[132:135], v[196:199], v[104:107]
	v_mfma_f32_16x16x32_bf16 v[100:103], v[140:143], v[196:199], v[100:103]
	v_mfma_f32_16x16x32_bf16 v[128:131], v[136:139], v[152:155], v[128:131]
	v_mfma_f32_16x16x32_bf16 v[124:127], v[144:147], v[152:155], v[124:127]
	v_mfma_f32_16x16x32_bf16 v[120:123], v[136:139], v[160:163], v[120:123]
	v_mfma_f32_16x16x32_bf16 v[116:119], v[144:147], v[160:163], v[116:119]
	v_mfma_f32_16x16x32_bf16 v[112:115], v[136:139], v[192:195], v[112:115]
	v_mfma_f32_16x16x32_bf16 v[108:111], v[144:147], v[192:195], v[108:111]
	v_mfma_f32_16x16x32_bf16 v[104:107], v[136:139], v[200:203], v[104:107]
	v_mfma_f32_16x16x32_bf16 v[100:103], v[144:147], v[200:203], v[100:103]
	s_barrier
	s_add_i32 s16, 0, 0x1c000
	s_add_i32 s17, s36, s18
	v_add_u32_e32 v2, s16, v243
	v_lshl_add_u64 v[168:169], v[168:169], 0, s[28:29]
	s_mov_b32 m0, s17
	ds_read_b128 v[204:207], v2
	ds_read_b128 v[208:211], v2 offset:1024
	ds_read_b128 v[220:223], v2 offset:2048
	ds_read_b128 v[234:237], v2 offset:3072
	global_load_lds_dwordx4 v[168:169], off
	v_lshl_add_u64 v[168:169], v[238:239], 0, s[28:29]
	s_add_i32 m0, s17, 0x2000
	s_nop 0
	global_load_lds_dwordx4 v[168:169], off
	s_barrier
	s_waitcnt lgkmcnt(0)
	s_waitcnt lgkmcnt(0)
	v_mfma_f32_16x16x32_bf16 v[64:67], v[204:207], v[148:151], v[64:67]
	v_mfma_f32_16x16x32_bf16 v[60:63], v[220:223], v[148:151], v[60:63]
	v_mfma_f32_16x16x32_bf16 v[56:59], v[204:207], v[156:159], v[56:59]
	v_mfma_f32_16x16x32_bf16 v[52:55], v[220:223], v[156:159], v[52:55]
	v_mfma_f32_16x16x32_bf16 v[48:51], v[204:207], v[188:191], v[48:51]
	v_mfma_f32_16x16x32_bf16 v[44:47], v[220:223], v[188:191], v[44:47]
	v_mfma_f32_16x16x32_bf16 v[40:43], v[204:207], v[196:199], v[40:43]
	v_mfma_f32_16x16x32_bf16 v[36:39], v[220:223], v[196:199], v[36:39]
	v_mfma_f32_16x16x32_bf16 v[64:67], v[208:211], v[152:155], v[64:67]
	v_mfma_f32_16x16x32_bf16 v[60:63], v[234:237], v[152:155], v[60:63]
	v_mfma_f32_16x16x32_bf16 v[56:59], v[208:211], v[160:163], v[56:59]
	v_mfma_f32_16x16x32_bf16 v[52:55], v[234:237], v[160:163], v[52:55]
	v_mfma_f32_16x16x32_bf16 v[48:51], v[208:211], v[192:195], v[48:51]
	v_mfma_f32_16x16x32_bf16 v[44:47], v[234:237], v[192:195], v[44:47]
	v_mfma_f32_16x16x32_bf16 v[40:43], v[208:211], v[200:203], v[40:43]
	v_mfma_f32_16x16x32_bf16 v[36:39], v[234:237], v[200:203], v[36:39]
	s_mov_b32 m0, s76
	v_lshl_add_u64 v[168:169], v[214:215], 0, s[28:29]
	s_barrier
	ds_read_b128 v[148:151], v245 offset:49152
	ds_read_b128 v[152:155], v245 offset:50176
	ds_read_b128 v[156:159], v245 offset:51200
	ds_read_b128 v[160:163], v245 offset:52224
	ds_read_b128 v[188:191], v245 offset:53248
	ds_read_b128 v[192:195], v245 offset:54272
	ds_read_b128 v[196:199], v245 offset:55296
	ds_read_b128 v[200:203], v245 offset:56320
	global_load_lds_dwordx4 v[168:169], off
	v_lshl_add_u64 v[168:169], v[224:225], 0, s[28:29]
	s_mov_b32 m0, s77
	s_nop 0
	global_load_lds_dwordx4 v[168:169], off
	s_barrier
	s_waitcnt lgkmcnt(0)
	s_waitcnt lgkmcnt(0)
	v_mfma_f32_16x16x32_bf16 v[96:99], v[132:135], v[148:151], v[96:99]
	v_mfma_f32_16x16x32_bf16 v[92:95], v[140:143], v[148:151], v[92:95]
	v_mfma_f32_16x16x32_bf16 v[88:91], v[132:135], v[156:159], v[88:91]
	v_mfma_f32_16x16x32_bf16 v[84:87], v[140:143], v[156:159], v[84:87]
	v_mfma_f32_16x16x32_bf16 v[80:83], v[132:135], v[188:191], v[80:83]
	v_mfma_f32_16x16x32_bf16 v[76:79], v[140:143], v[188:191], v[76:79]
	v_mfma_f32_16x16x32_bf16 v[72:75], v[132:135], v[196:199], v[72:75]
	v_mfma_f32_16x16x32_bf16 v[68:71], v[140:143], v[196:199], v[68:71]
	v_mfma_f32_16x16x32_bf16 v[96:99], v[136:139], v[152:155], v[96:99]
	v_mfma_f32_16x16x32_bf16 v[92:95], v[144:147], v[152:155], v[92:95]
	v_mfma_f32_16x16x32_bf16 v[88:91], v[136:139], v[160:163], v[88:91]
	v_mfma_f32_16x16x32_bf16 v[84:87], v[144:147], v[160:163], v[84:87]
	v_mfma_f32_16x16x32_bf16 v[80:83], v[136:139], v[192:195], v[80:83]
	v_mfma_f32_16x16x32_bf16 v[76:79], v[144:147], v[192:195], v[76:79]
	v_mfma_f32_16x16x32_bf16 v[72:75], v[136:139], v[200:203], v[72:75]
	v_mfma_f32_16x16x32_bf16 v[68:71], v[144:147], v[200:203], v[68:71]
	s_barrier
	s_add_u32 s4, s4, 0x40080
	s_addc_u32 s5, s5, 0
	s_add_i32 s16, s16, s18
	v_lshl_add_u64 v[132:133], s[4:5], 0, v[172:173]
	s_mov_b32 m0, s16
	s_nop 0
	global_load_lds_dwordx4 v[132:133], off
	v_lshl_add_u64 v[132:133], s[4:5], 0, v[176:177]
	s_add_i32 m0, s16, 0x2000
	s_nop 0
	global_load_lds_dwordx4 v[132:133], off
	s_waitcnt vmcnt(6)
	s_barrier
	v_mfma_f32_16x16x32_bf16 v[32:35], v[204:207], v[148:151], v[32:35]
	v_mfma_f32_16x16x32_bf16 v[28:31], v[220:223], v[148:151], v[28:31]
	v_mfma_f32_16x16x32_bf16 v[24:27], v[204:207], v[156:159], v[24:27]
	v_mfma_f32_16x16x32_bf16 v[20:23], v[220:223], v[156:159], v[20:23]
	v_mfma_f32_16x16x32_bf16 v[16:19], v[204:207], v[188:191], v[16:19]
	v_mfma_f32_16x16x32_bf16 v[12:15], v[220:223], v[188:191], v[12:15]
	v_mfma_f32_16x16x32_bf16 v[8:11], v[204:207], v[196:199], v[8:11]
	v_mfma_f32_16x16x32_bf16 v[4:7], v[220:223], v[196:199], v[4:7]
	v_mfma_f32_16x16x32_bf16 v[32:35], v[208:211], v[152:155], v[32:35]
	v_mfma_f32_16x16x32_bf16 v[28:31], v[234:237], v[152:155], v[28:31]
	v_mfma_f32_16x16x32_bf16 v[24:27], v[208:211], v[160:163], v[24:27]
	v_mfma_f32_16x16x32_bf16 v[20:23], v[234:237], v[160:163], v[20:23]
	v_mfma_f32_16x16x32_bf16 v[16:19], v[208:211], v[192:195], v[16:19]
	v_mfma_f32_16x16x32_bf16 v[12:15], v[234:237], v[192:195], v[12:15]
	v_mfma_f32_16x16x32_bf16 v[8:11], v[208:211], v[200:203], v[8:11]
	v_mfma_f32_16x16x32_bf16 v[4:7], v[234:237], v[200:203], v[4:7]
	s_add_i32 s21, s21, 2
	s_add_u32 s0, s0, 0x100
	s_addc_u32 s1, s1, 0
	s_add_u32 s3, s3, 0x100
	s_addc_u32 s20, s20, 0
	s_cmp_gt_u32 s21, 13
	s_barrier
	s_cbranch_scc0 .LBB0_54
	s_lshl_b32 s74, s2, 8
	s_cmp_lt_i32 s2, 2
	s_mov_b32 s2, 0
	s_movk_i32 s20, 0x4000
	s_cbranch_scc1 .LBB0_60
	s_cmpk_lt_u32 s74, 0x400
	s_mov_b32 s2, 1
	s_cbranch_scc1 .LBB0_60
	s_cmpk_lt_u32 s74, 0x800
	s_mov_b32 s2, 2
	s_cbranch_scc1 .LBB0_60
	s_cmpk_lt_u32 s74, 0xc00
	s_mov_b32 s2, 3
	s_cbranch_scc1 .LBB0_60
	s_cmpk_lt_u32 s74, 0x1300
	s_cselect_b32 s0, 7, 8
	s_cmpk_gt_u32 s74, 0xeff
	s_cselect_b32 s0, s0, 6
	s_cmpk_gt_u32 s74, 0xe7f
	s_cselect_b32 s0, s0, 5
	s_cmpk_gt_u32 s74, 0xdff
	s_cselect_b32 s2, s0, 4

.LBB0_632:
	s_add_i32 s51, s16, 2
	s_add_u32 s4, s2, 0x100
	s_addc_u32 s5, s3, 0
	s_add_i32 s52, 0, 0x10000
	v_add_u32_e32 v144, s52, v196
	ds_read_b128 v[132:135], v144
	ds_read_b128 v[136:139], v144 offset:1024
	ds_read_b128 v[140:143], v144 offset:2048
	ds_read_b128 v[144:147], v144 offset:3072
	s_cmp_eq_u32 s48, s16
	s_cselect_b32 s16, s0, s4
	s_cselect_b32 s17, s1, s5
	s_cselect_b32 s21, s9, s50
	s_cselect_b32 s20, s8, s49
	v_lshl_add_u64 v[168:169], s[2:3], 0, v[176:177]
	s_add_i32 m0, s23, 0xc000
	ds_read_b128 v[148:151], v198
	ds_read_b128 v[152:155], v198 offset:1024
	ds_read_b128 v[156:159], v198 offset:2048
	ds_read_b128 v[160:163], v198 offset:3072
	ds_read_b128 v[180:183], v198 offset:4096
	ds_read_b128 v[184:187], v198 offset:5120
	ds_read_b128 v[188:191], v198 offset:6144
	ds_read_b128 v[192:195], v198 offset:7168
	global_load_lds_dwordx4 v[168:169], off
	v_lshl_add_u64 v[168:169], s[2:3], 0, v[178:179]
	s_add_i32 m0, s23, 0xe000
	s_nop 0
	global_load_lds_dwordx4 v[168:169], off
	s_waitcnt lgkmcnt(8)
	s_barrier
	s_waitcnt lgkmcnt(0)
	s_waitcnt lgkmcnt(0)
	v_mfma_f32_16x16x32_bf16 v[128:131], v[132:135], v[148:151], v[128:131]
	v_mfma_f32_16x16x32_bf16 v[124:127], v[140:143], v[148:151], v[124:127]
	v_mfma_f32_16x16x32_bf16 v[120:123], v[132:135], v[156:159], v[120:123]
	v_mfma_f32_16x16x32_bf16 v[116:119], v[140:143], v[156:159], v[116:119]
	v_mfma_f32_16x16x32_bf16 v[112:115], v[132:135], v[180:183], v[112:115]
	v_mfma_f32_16x16x32_bf16 v[108:111], v[140:143], v[180:183], v[108:111]
	v_mfma_f32_16x16x32_bf16 v[104:107], v[132:135], v[188:191], v[104:107]
	v_mfma_f32_16x16x32_bf16 v[100:103], v[140:143], v[188:191], v[100:103]
	v_mfma_f32_16x16x32_bf16 v[128:131], v[136:139], v[152:155], v[128:131]
	v_mfma_f32_16x16x32_bf16 v[124:127], v[144:147], v[152:155], v[124:127]
	v_mfma_f32_16x16x32_bf16 v[120:123], v[136:139], v[160:163], v[120:123]
	v_mfma_f32_16x16x32_bf16 v[116:119], v[144:147], v[160:163], v[116:119]
	v_mfma_f32_16x16x32_bf16 v[112:115], v[136:139], v[184:187], v[112:115]
	v_mfma_f32_16x16x32_bf16 v[108:111], v[144:147], v[184:187], v[108:111]
	v_mfma_f32_16x16x32_bf16 v[104:107], v[136:139], v[192:195], v[104:107]
	v_mfma_f32_16x16x32_bf16 v[100:103], v[144:147], v[192:195], v[100:103]
	s_barrier
	s_add_i32 s53, 0, 0x14000
	v_add_u32_e32 v168, s53, v196
	s_add_i32 s2, s52, s22
	ds_read_b128 v[200:203], v168
	ds_read_b128 v[204:207], v168 offset:1024
	ds_read_b128 v[208:211], v168 offset:2048
	ds_read_b128 v[220:223], v168 offset:3072
	v_lshl_add_u64 v[168:169], s[20:21], 0, v[2:3]
	s_mov_b32 m0, s2
	v_lshl_add_u64 v[214:215], s[20:21], 0, v[174:175]
	global_load_lds_dwordx4 v[168:169], off
	s_add_i32 m0, s2, 0x2000
	s_nop 0
	global_load_lds_dwordx4 v[214:215], off
	s_barrier
	s_waitcnt lgkmcnt(0)
	s_waitcnt lgkmcnt(0)
	v_mfma_f32_16x16x32_bf16 v[96:99], v[200:203], v[148:151], v[96:99]
	v_mfma_f32_16x16x32_bf16 v[92:95], v[208:211], v[148:151], v[92:95]
	v_mfma_f32_16x16x32_bf16 v[88:91], v[200:203], v[156:159], v[88:91]
	v_mfma_f32_16x16x32_bf16 v[84:87], v[208:211], v[156:159], v[84:87]
	v_mfma_f32_16x16x32_bf16 v[80:83], v[200:203], v[180:183], v[80:83]
	v_mfma_f32_16x16x32_bf16 v[76:79], v[208:211], v[180:183], v[76:79]
	v_mfma_f32_16x16x32_bf16 v[72:75], v[200:203], v[188:191], v[72:75]
	v_mfma_f32_16x16x32_bf16 v[68:71], v[208:211], v[188:191], v[68:71]
	v_mfma_f32_16x16x32_bf16 v[96:99], v[204:207], v[152:155], v[96:99]
	v_mfma_f32_16x16x32_bf16 v[92:95], v[220:223], v[152:155], v[92:95]
	v_mfma_f32_16x16x32_bf16 v[88:91], v[204:207], v[160:163], v[88:91]
	v_mfma_f32_16x16x32_bf16 v[84:87], v[220:223], v[160:163], v[84:87]
	v_mfma_f32_16x16x32_bf16 v[80:83], v[204:207], v[184:187], v[80:83]
	v_mfma_f32_16x16x32_bf16 v[76:79], v[220:223], v[184:187], v[76:79]
	v_mfma_f32_16x16x32_bf16 v[72:75], v[204:207], v[192:195], v[72:75]
	v_mfma_f32_16x16x32_bf16 v[68:71], v[220:223], v[192:195], v[68:71]
	s_mov_b32 m0, s23
	v_lshl_add_u64 v[224:225], s[16:17], 0, v[0:1]
	s_barrier
	ds_read_b128 v[148:151], v198 offset:16384
	ds_read_b128 v[152:155], v198 offset:17408
	ds_read_b128 v[156:159], v198 offset:18432
	ds_read_b128 v[160:163], v198 offset:19456
	ds_read_b128 v[180:183], v198 offset:20480
	ds_read_b128 v[184:187], v198 offset:21504
	ds_read_b128 v[188:191], v198 offset:22528
	ds_read_b128 v[192:195], v198 offset:23552
	global_load_lds_dwordx4 v[224:225], off
	v_lshl_add_u64 v[234:235], s[16:17], 0, v[172:173]
	s_mov_b32 m0, s26
	s_nop 0
	global_load_lds_dwordx4 v[234:235], off
	s_barrier
	s_waitcnt lgkmcnt(0)
	s_waitcnt lgkmcnt(0)
	v_mfma_f32_16x16x32_bf16 v[64:67], v[132:135], v[148:151], v[64:67]
	v_mfma_f32_16x16x32_bf16 v[60:63], v[140:143], v[148:151], v[60:63]
	v_mfma_f32_16x16x32_bf16 v[56:59], v[132:135], v[156:159], v[56:59]
	v_mfma_f32_16x16x32_bf16 v[52:55], v[140:143], v[156:159], v[52:55]
	v_mfma_f32_16x16x32_bf16 v[48:51], v[132:135], v[180:183], v[48:51]
	v_mfma_f32_16x16x32_bf16 v[44:47], v[140:143], v[180:183], v[44:47]
	v_mfma_f32_16x16x32_bf16 v[40:43], v[132:135], v[188:191], v[40:43]
	v_mfma_f32_16x16x32_bf16 v[36:39], v[140:143], v[188:191], v[36:39]
	v_mfma_f32_16x16x32_bf16 v[64:67], v[136:139], v[152:155], v[64:67]
	v_mfma_f32_16x16x32_bf16 v[60:63], v[144:147], v[152:155], v[60:63]
	v_mfma_f32_16x16x32_bf16 v[56:59], v[136:139], v[160:163], v[56:59]
	v_mfma_f32_16x16x32_bf16 v[52:55], v[144:147], v[160:163], v[52:55]
	v_mfma_f32_16x16x32_bf16 v[48:51], v[136:139], v[184:187], v[48:51]
	v_mfma_f32_16x16x32_bf16 v[44:47], v[144:147], v[184:187], v[44:47]
	v_mfma_f32_16x16x32_bf16 v[40:43], v[136:139], v[192:195], v[40:43]
	v_mfma_f32_16x16x32_bf16 v[36:39], v[144:147], v[192:195], v[36:39]
	s_barrier
	s_add_u32 s2, s20, 0x60000
	s_addc_u32 s3, s21, 0
	s_add_i32 s52, s53, s22
	v_lshl_add_u64 v[132:133], s[2:3], 0, v[2:3]
	s_mov_b32 m0, s52
	s_nop 0
	global_load_lds_dwordx4 v[132:133], off
	v_lshl_add_u64 v[132:133], s[2:3], 0, v[174:175]
	s_add_i32 m0, s52, 0x2000
	s_nop 0
	global_load_lds_dwordx4 v[132:133], off
	s_waitcnt vmcnt(6)
	s_barrier
	v_mfma_f32_16x16x32_bf16 v[32:35], v[200:203], v[148:151], v[32:35]
	v_mfma_f32_16x16x32_bf16 v[28:31], v[208:211], v[148:151], v[28:31]
	v_mfma_f32_16x16x32_bf16 v[24:27], v[200:203], v[156:159], v[24:27]
	v_mfma_f32_16x16x32_bf16 v[20:23], v[208:211], v[156:159], v[20:23]
	v_mfma_f32_16x16x32_bf16 v[16:19], v[200:203], v[180:183], v[16:19]
	v_mfma_f32_16x16x32_bf16 v[12:15], v[208:211], v[180:183], v[12:15]
	v_mfma_f32_16x16x32_bf16 v[8:11], v[200:203], v[188:191], v[8:11]
	v_mfma_f32_16x16x32_bf16 v[4:7], v[208:211], v[188:191], v[4:7]
	v_mfma_f32_16x16x32_bf16 v[32:35], v[204:207], v[152:155], v[32:35]
	v_mfma_f32_16x16x32_bf16 v[28:31], v[220:223], v[152:155], v[28:31]
	v_mfma_f32_16x16x32_bf16 v[24:27], v[204:207], v[160:163], v[24:27]
	v_mfma_f32_16x16x32_bf16 v[20:23], v[220:223], v[160:163], v[20:23]
	v_mfma_f32_16x16x32_bf16 v[16:19], v[204:207], v[184:187], v[16:19]
	v_mfma_f32_16x16x32_bf16 v[12:15], v[220:223], v[184:187], v[12:15]
	v_mfma_f32_16x16x32_bf16 v[8:11], v[204:207], v[192:195], v[8:11]
	v_mfma_f32_16x16x32_bf16 v[4:7], v[220:223], v[192:195], v[4:7]
	s_add_i32 s52, 0, 0x18000
	v_add_u32_e32 v144, s52, v196
	s_barrier
	ds_read_b128 v[132:135], v144
	ds_read_b128 v[136:139], v144 offset:1024
	ds_read_b128 v[140:143], v144 offset:2048
	ds_read_b128 v[144:147], v144 offset:3072
	s_add_u32 s2, s16, 0x60000
	s_addc_u32 s3, s17, 0
	s_mov_b32 m0, s27
	v_lshl_add_u64 v[200:201], s[2:3], 0, v[0:1]
	ds_read_b128 v[148:151], v198 offset:32768
	ds_read_b128 v[152:155], v198 offset:33792
	ds_read_b128 v[156:159], v198 offset:34816
	ds_read_b128 v[160:163], v198 offset:35840
	ds_read_b128 v[180:183], v198 offset:36864
	ds_read_b128 v[184:187], v198 offset:37888
	ds_read_b128 v[188:191], v198 offset:38912
	ds_read_b128 v[192:195], v198 offset:39936
	global_load_lds_dwordx4 v[200:201], off
	v_lshl_add_u64 v[200:201], s[2:3], 0, v[172:173]
	s_mov_b32 m0, s30
	s_nop 0
	global_load_lds_dwordx4 v[200:201], off
	s_waitcnt lgkmcnt(8)
	s_barrier
	s_waitcnt lgkmcnt(0)
	s_waitcnt lgkmcnt(0)
	v_mfma_f32_16x16x32_bf16 v[128:131], v[132:135], v[148:151], v[128:131]
	v_mfma_f32_16x16x32_bf16 v[124:127], v[140:143], v[148:151], v[124:127]
	v_mfma_f32_16x16x32_bf16 v[120:123], v[132:135], v[156:159], v[120:123]
	v_mfma_f32_16x16x32_bf16 v[116:119], v[140:143], v[156:159], v[116:119]
	v_mfma_f32_16x16x32_bf16 v[112:115], v[132:135], v[180:183], v[112:115]
	v_mfma_f32_16x16x32_bf16 v[108:111], v[140:143], v[180:183], v[108:111]
	v_mfma_f32_16x16x32_bf16 v[104:107], v[132:135], v[188:191], v[104:107]
	v_mfma_f32_16x16x32_bf16 v[100:103], v[140:143], v[188:191], v[100:103]
	v_mfma_f32_16x16x32_bf16 v[128:131], v[136:139], v[152:155], v[128:131]
	v_mfma_f32_16x16x32_bf16 v[124:127], v[144:147], v[152:155], v[124:127]
	v_mfma_f32_16x16x32_bf16 v[120:123], v[136:139], v[160:163], v[120:123]
	v_mfma_f32_16x16x32_bf16 v[116:119], v[144:147], v[160:163], v[116:119]
	v_mfma_f32_16x16x32_bf16 v[112:115], v[136:139], v[184:187], v[112:115]
	v_mfma_f32_16x16x32_bf16 v[108:111], v[144:147], v[184:187], v[108:111]
	v_mfma_f32_16x16x32_bf16 v[104:107], v[136:139], v[192:195], v[104:107]
	v_mfma_f32_16x16x32_bf16 v[100:103], v[144:147], v[192:195], v[100:103]
	s_barrier
	s_add_i32 s16, 0, 0x1c000
	s_add_i32 s2, s52, s22
	v_add_u32_e32 v199, s16, v196
	v_lshl_add_u64 v[168:169], v[168:169], 0, s[28:29]
	s_mov_b32 m0, s2
	ds_read_b128 v[200:203], v199
	ds_read_b128 v[204:207], v199 offset:1024
	ds_read_b128 v[208:211], v199 offset:2048
	ds_read_b128 v[220:223], v199 offset:3072
	global_load_lds_dwordx4 v[168:169], off
	v_lshl_add_u64 v[168:169], v[214:215], 0, s[28:29]
	s_add_i32 m0, s2, 0x2000
	s_nop 0
	global_load_lds_dwordx4 v[168:169], off
	s_barrier
	s_waitcnt lgkmcnt(0)
	s_waitcnt lgkmcnt(0)
	v_mfma_f32_16x16x32_bf16 v[96:99], v[200:203], v[148:151], v[96:99]
	v_mfma_f32_16x16x32_bf16 v[92:95], v[208:211], v[148:151], v[92:95]
	v_mfma_f32_16x16x32_bf16 v[88:91], v[200:203], v[156:159], v[88:91]
	v_mfma_f32_16x16x32_bf16 v[84:87], v[208:211], v[156:159], v[84:87]
	v_mfma_f32_16x16x32_bf16 v[80:83], v[200:203], v[180:183], v[80:83]
	v_mfma_f32_16x16x32_bf16 v[76:79], v[208:211], v[180:183], v[76:79]
	v_mfma_f32_16x16x32_bf16 v[72:75], v[200:203], v[188:191], v[72:75]
	v_mfma_f32_16x16x32_bf16 v[68:71], v[208:211], v[188:191], v[68:71]
	v_mfma_f32_16x16x32_bf16 v[96:99], v[204:207], v[152:155], v[96:99]
	v_mfma_f32_16x16x32_bf16 v[92:95], v[220:223], v[152:155], v[92:95]
	v_mfma_f32_16x16x32_bf16 v[88:91], v[204:207], v[160:163], v[88:91]
	v_mfma_f32_16x16x32_bf16 v[84:87], v[220:223], v[160:163], v[84:87]
	v_mfma_f32_16x16x32_bf16 v[80:83], v[204:207], v[184:187], v[80:83]
	v_mfma_f32_16x16x32_bf16 v[76:79], v[220:223], v[184:187], v[76:79]
	v_mfma_f32_16x16x32_bf16 v[72:75], v[204:207], v[192:195], v[72:75]
	v_mfma_f32_16x16x32_bf16 v[68:71], v[220:223], v[192:195], v[68:71]
	s_mov_b32 m0, s31
	v_lshl_add_u64 v[168:169], v[224:225], 0, s[28:29]
	s_barrier
	ds_read_b128 v[148:151], v198 offset:49152
	ds_read_b128 v[152:155], v198 offset:50176
	ds_read_b128 v[156:159], v198 offset:51200
	ds_read_b128 v[160:163], v198 offset:52224
	ds_read_b128 v[180:183], v198 offset:53248
	ds_read_b128 v[184:187], v198 offset:54272
	ds_read_b128 v[188:191], v198 offset:55296
	ds_read_b128 v[192:195], v198 offset:56320
	global_load_lds_dwordx4 v[168:169], off
	v_lshl_add_u64 v[168:169], v[234:235], 0, s[28:29]
	s_mov_b32 m0, s42
	s_nop 0
	global_load_lds_dwordx4 v[168:169], off
	s_barrier
	s_waitcnt lgkmcnt(0)
	s_waitcnt lgkmcnt(0)
	v_mfma_f32_16x16x32_bf16 v[64:67], v[132:135], v[148:151], v[64:67]
	v_mfma_f32_16x16x32_bf16 v[60:63], v[140:143], v[148:151], v[60:63]
	v_mfma_f32_16x16x32_bf16 v[56:59], v[132:135], v[156:159], v[56:59]
	v_mfma_f32_16x16x32_bf16 v[52:55], v[140:143], v[156:159], v[52:55]
	v_mfma_f32_16x16x32_bf16 v[48:51], v[132:135], v[180:183], v[48:51]
	v_mfma_f32_16x16x32_bf16 v[44:47], v[140:143], v[180:183], v[44:47]
	v_mfma_f32_16x16x32_bf16 v[40:43], v[132:135], v[188:191], v[40:43]
	v_mfma_f32_16x16x32_bf16 v[36:39], v[140:143], v[188:191], v[36:39]
	v_mfma_f32_16x16x32_bf16 v[64:67], v[136:139], v[152:155], v[64:67]
	v_mfma_f32_16x16x32_bf16 v[60:63], v[144:147], v[152:155], v[60:63]
	v_mfma_f32_16x16x32_bf16 v[56:59], v[136:139], v[160:163], v[56:59]
	v_mfma_f32_16x16x32_bf16 v[52:55], v[144:147], v[160:163], v[52:55]
	v_mfma_f32_16x16x32_bf16 v[48:51], v[136:139], v[184:187], v[48:51]
	v_mfma_f32_16x16x32_bf16 v[44:47], v[144:147], v[184:187], v[44:47]
	v_mfma_f32_16x16x32_bf16 v[40:43], v[136:139], v[192:195], v[40:43]
	v_mfma_f32_16x16x32_bf16 v[36:39], v[144:147], v[192:195], v[36:39]
	s_barrier
	s_add_u32 s2, s20, 0x60080
	s_addc_u32 s3, s21, 0
	s_add_i32 s16, s16, s22
	v_lshl_add_u64 v[132:133], s[2:3], 0, v[2:3]
	s_mov_b32 m0, s16
	s_nop 0
	global_load_lds_dwordx4 v[132:133], off
	v_lshl_add_u64 v[132:133], s[2:3], 0, v[174:175]
	s_add_i32 m0, s16, 0x2000
	s_nop 0
	global_load_lds_dwordx4 v[132:133], off
	s_waitcnt vmcnt(6)
	s_barrier
	v_mfma_f32_16x16x32_bf16 v[32:35], v[200:203], v[148:151], v[32:35]
	v_mfma_f32_16x16x32_bf16 v[28:31], v[208:211], v[148:151], v[28:31]
	v_mfma_f32_16x16x32_bf16 v[24:27], v[200:203], v[156:159], v[24:27]
	v_mfma_f32_16x16x32_bf16 v[20:23], v[208:211], v[156:159], v[20:23]
	v_mfma_f32_16x16x32_bf16 v[16:19], v[200:203], v[180:183], v[16:19]
	v_mfma_f32_16x16x32_bf16 v[12:15], v[208:211], v[180:183], v[12:15]
	v_mfma_f32_16x16x32_bf16 v[8:11], v[200:203], v[188:191], v[8:11]
	v_mfma_f32_16x16x32_bf16 v[4:7], v[208:211], v[188:191], v[4:7]
	v_mfma_f32_16x16x32_bf16 v[32:35], v[204:207], v[152:155], v[32:35]
	v_mfma_f32_16x16x32_bf16 v[28:31], v[220:223], v[152:155], v[28:31]
	v_mfma_f32_16x16x32_bf16 v[24:27], v[204:207], v[160:163], v[24:27]
	v_mfma_f32_16x16x32_bf16 v[20:23], v[220:223], v[160:163], v[20:23]
	v_mfma_f32_16x16x32_bf16 v[16:19], v[204:207], v[184:187], v[16:19]
	v_mfma_f32_16x16x32_bf16 v[12:15], v[220:223], v[184:187], v[12:15]
	v_mfma_f32_16x16x32_bf16 v[8:11], v[204:207], v[192:195], v[8:11]
	v_mfma_f32_16x16x32_bf16 v[4:7], v[220:223], v[192:195], v[4:7]
	s_add_u32 s49, s49, 0x100
	s_addc_u32 s50, s50, 0
	s_cmp_ge_i32 s51, s40
	s_mov_b64 s[2:3], s[4:5]
	s_mov_b32 s16, s51
	s_barrier
	s_cbranch_scc0 .LBB0_632
	v_lshl_add_u32 v182, s41, 8, v170
	v_ashrrev_i32_e32 v183, 31, v182
	v_lshl_or_b32 v186, s37, 8, v197
	v_lshlrev_b64 v[184:185], 10, v[182:183]
	v_ashrrev_i32_e32 v187, 31, v186
	v_lshl_add_u64 v[180:181], v[184:185], 0, v[186:187]
	v_readlane_b32 s2, v252, 60
	v_lshlrev_b64 v[134:135], 1, v[180:181]
	v_readlane_b32 s3, v252, 61
	s_cmp_lg_u32 s36, 0
	s_nop 0
	v_lshl_add_u64 v[132:133], s[2:3], 0, v[134:135]
	global_load_dwordx4 v[160:163], v[132:133], off
	s_cselect_b64 s[2:3], -1, 0
	s_and_b64 vcc, exec, s[2:3]
	s_cbranch_vccz .LBB0_635
	s_mov_b64 s[4:5], 0
	s_waitcnt vmcnt(0)
	v_mov_b32_e32 v155, v163
	v_mov_b32_e32 v154, v162
	v_mov_b32_e32 v153, v161
	v_mov_b32_e32 v152, v160
	s_branch .LBB0_636

.LBB0_840:
	s_add_u32 s16, s10, 0xfffc0080
	s_addc_u32 s17, s11, -1
	s_add_i32 s45, 0, 0x10000
	v_add_u32_e32 v147, s45, v141
	ds_read_b128 v[148:151], v147
	ds_read_b128 v[152:155], v147 offset:1024
	ds_read_b128 v[156:159], v147 offset:2048
	ds_read_b128 v[160:163], v147 offset:3072
	s_cmp_eq_u32 s44, 12
	s_cselect_b32 s17, s5, s17
	s_cselect_b32 s16, s4, s16
	s_cselect_b32 s21, s9, s3
	s_cselect_b32 s20, s8, s1
	v_lshl_add_u64 v[168:169], s[10:11], 0, v[136:137]
	s_add_i32 m0, s23, 0xc000
	ds_read_b128 v[172:175], v146
	ds_read_b128 v[176:179], v146 offset:1024
	ds_read_b128 v[180:183], v146 offset:2048
	ds_read_b128 v[184:187], v146 offset:3072
	ds_read_b128 v[188:191], v146 offset:4096
	ds_read_b128 v[192:195], v146 offset:5120
	ds_read_b128 v[196:199], v146 offset:6144
	ds_read_b128 v[200:203], v146 offset:7168
	global_load_lds_dwordx4 v[168:169], off
	v_lshl_add_u64 v[168:169], s[10:11], 0, v[138:139]
	s_add_i32 m0, s23, 0xe000
	s_nop 0
	global_load_lds_dwordx4 v[168:169], off
	s_waitcnt lgkmcnt(8)
	s_barrier
	s_waitcnt lgkmcnt(0)
	s_waitcnt lgkmcnt(0)
	v_mfma_f32_16x16x32_bf16 v[128:131], v[148:151], v[172:175], v[128:131]
	v_mfma_f32_16x16x32_bf16 v[124:127], v[156:159], v[172:175], v[124:127]
	v_mfma_f32_16x16x32_bf16 v[120:123], v[148:151], v[180:183], v[120:123]
	v_mfma_f32_16x16x32_bf16 v[116:119], v[156:159], v[180:183], v[116:119]
	v_mfma_f32_16x16x32_bf16 v[112:115], v[148:151], v[188:191], v[112:115]
	v_mfma_f32_16x16x32_bf16 v[108:111], v[156:159], v[188:191], v[108:111]
	v_mfma_f32_16x16x32_bf16 v[104:107], v[148:151], v[196:199], v[104:107]
	v_mfma_f32_16x16x32_bf16 v[100:103], v[156:159], v[196:199], v[100:103]
	v_mfma_f32_16x16x32_bf16 v[128:131], v[152:155], v[176:179], v[128:131]
	v_mfma_f32_16x16x32_bf16 v[124:127], v[160:163], v[176:179], v[124:127]
	v_mfma_f32_16x16x32_bf16 v[120:123], v[152:155], v[184:187], v[120:123]
	v_mfma_f32_16x16x32_bf16 v[116:119], v[160:163], v[184:187], v[116:119]
	v_mfma_f32_16x16x32_bf16 v[112:115], v[152:155], v[192:195], v[112:115]
	v_mfma_f32_16x16x32_bf16 v[108:111], v[160:163], v[192:195], v[108:111]
	v_mfma_f32_16x16x32_bf16 v[104:107], v[152:155], v[200:203], v[104:107]
	v_mfma_f32_16x16x32_bf16 v[100:103], v[160:163], v[200:203], v[100:103]
	s_barrier
	s_add_i32 s50, 0, 0x14000
	s_add_i32 s45, s45, s22
	v_add_u32_e32 v147, s50, v141
	v_lshl_add_u64 v[168:169], s[20:21], 0, v[2:3]
	s_mov_b32 m0, s45
	ds_read_b128 v[204:207], v147
	ds_read_b128 v[208:211], v147 offset:1024
	ds_read_b128 v[220:223], v147 offset:2048
	ds_read_b128 v[234:237], v147 offset:3072
	global_load_lds_dwordx4 v[168:169], off
	v_lshl_add_u64 v[214:215], s[20:21], 0, v[0:1]
	s_add_i32 m0, s45, 0x2000
	s_nop 0
	global_load_lds_dwordx4 v[214:215], off
	s_barrier
	s_waitcnt lgkmcnt(0)
	s_waitcnt lgkmcnt(0)
	v_mfma_f32_16x16x32_bf16 v[84:87], v[204:207], v[172:175], v[84:87]
	v_mfma_f32_16x16x32_bf16 v[76:79], v[220:223], v[172:175], v[76:79]
	v_mfma_f32_16x16x32_bf16 v[72:75], v[204:207], v[180:183], v[72:75]
	v_mfma_f32_16x16x32_bf16 v[68:71], v[220:223], v[180:183], v[68:71]
	v_mfma_f32_16x16x32_bf16 v[56:59], v[204:207], v[188:191], v[56:59]
	v_mfma_f32_16x16x32_bf16 v[52:55], v[220:223], v[188:191], v[52:55]
	v_mfma_f32_16x16x32_bf16 v[44:47], v[204:207], v[196:199], v[44:47]
	v_mfma_f32_16x16x32_bf16 v[36:39], v[220:223], v[196:199], v[36:39]
	v_mfma_f32_16x16x32_bf16 v[84:87], v[208:211], v[176:179], v[84:87]
	v_mfma_f32_16x16x32_bf16 v[76:79], v[234:237], v[176:179], v[76:79]
	v_mfma_f32_16x16x32_bf16 v[72:75], v[208:211], v[184:187], v[72:75]
	v_mfma_f32_16x16x32_bf16 v[68:71], v[234:237], v[184:187], v[68:71]
	v_mfma_f32_16x16x32_bf16 v[56:59], v[208:211], v[192:195], v[56:59]
	v_mfma_f32_16x16x32_bf16 v[52:55], v[234:237], v[192:195], v[52:55]
	v_mfma_f32_16x16x32_bf16 v[44:47], v[208:211], v[200:203], v[44:47]
	v_mfma_f32_16x16x32_bf16 v[36:39], v[234:237], v[200:203], v[36:39]
	s_mov_b32 m0, s23
	v_lshl_add_u64 v[224:225], s[16:17], 0, v[134:135]
	s_barrier
	ds_read_b128 v[172:175], v146 offset:16384
	ds_read_b128 v[176:179], v146 offset:17408
	ds_read_b128 v[180:183], v146 offset:18432
	ds_read_b128 v[184:187], v146 offset:19456
	ds_read_b128 v[188:191], v146 offset:20480
	ds_read_b128 v[192:195], v146 offset:21504
	ds_read_b128 v[196:199], v146 offset:22528
	ds_read_b128 v[200:203], v146 offset:23552
	global_load_lds_dwordx4 v[224:225], off
	v_lshl_add_u64 v[238:239], s[16:17], 0, v[132:133]
	s_mov_b32 m0, s26
	s_nop 0
	global_load_lds_dwordx4 v[238:239], off
	s_barrier
	s_waitcnt lgkmcnt(0)
	s_waitcnt lgkmcnt(0)
	v_mfma_f32_16x16x32_bf16 v[96:99], v[148:151], v[172:175], v[96:99]
	v_mfma_f32_16x16x32_bf16 v[92:95], v[156:159], v[172:175], v[92:95]
	v_mfma_f32_16x16x32_bf16 v[88:91], v[148:151], v[180:183], v[88:91]
	v_mfma_f32_16x16x32_bf16 v[80:83], v[156:159], v[180:183], v[80:83]
	v_mfma_f32_16x16x32_bf16 v[64:67], v[148:151], v[188:191], v[64:67]
	v_mfma_f32_16x16x32_bf16 v[60:63], v[156:159], v[188:191], v[60:63]
	v_mfma_f32_16x16x32_bf16 v[48:51], v[148:151], v[196:199], v[48:51]
	v_mfma_f32_16x16x32_bf16 v[40:43], v[156:159], v[196:199], v[40:43]
	v_mfma_f32_16x16x32_bf16 v[96:99], v[152:155], v[176:179], v[96:99]
	v_mfma_f32_16x16x32_bf16 v[92:95], v[160:163], v[176:179], v[92:95]
	v_mfma_f32_16x16x32_bf16 v[88:91], v[152:155], v[184:187], v[88:91]
	v_mfma_f32_16x16x32_bf16 v[80:83], v[160:163], v[184:187], v[80:83]
	v_mfma_f32_16x16x32_bf16 v[64:67], v[152:155], v[192:195], v[64:67]
	v_mfma_f32_16x16x32_bf16 v[60:63], v[160:163], v[192:195], v[60:63]
	v_mfma_f32_16x16x32_bf16 v[48:51], v[152:155], v[200:203], v[48:51]
	v_mfma_f32_16x16x32_bf16 v[40:43], v[160:163], v[200:203], v[40:43]
	s_barrier
	s_add_u32 s48, s20, 0x40000
	s_addc_u32 s49, s21, 0
	s_add_i32 s45, s50, s22
	v_lshl_add_u64 v[148:149], s[48:49], 0, v[2:3]
	s_mov_b32 m0, s45
	s_nop 0
	global_load_lds_dwordx4 v[148:149], off
	v_lshl_add_u64 v[148:149], s[48:49], 0, v[0:1]
	s_add_i32 m0, s45, 0x2000
	s_nop 0
	global_load_lds_dwordx4 v[148:149], off
	s_waitcnt vmcnt(6)
	s_barrier
	v_mfma_f32_16x16x32_bf16 v[32:35], v[204:207], v[172:175], v[32:35]
	v_mfma_f32_16x16x32_bf16 v[28:31], v[220:223], v[172:175], v[28:31]
	v_mfma_f32_16x16x32_bf16 v[24:27], v[204:207], v[180:183], v[24:27]
	v_mfma_f32_16x16x32_bf16 v[20:23], v[220:223], v[180:183], v[20:23]
	v_mfma_f32_16x16x32_bf16 v[16:19], v[204:207], v[188:191], v[16:19]
	v_mfma_f32_16x16x32_bf16 v[12:15], v[220:223], v[188:191], v[12:15]
	v_mfma_f32_16x16x32_bf16 v[8:11], v[204:207], v[196:199], v[8:11]
	v_mfma_f32_16x16x32_bf16 v[4:7], v[220:223], v[196:199], v[4:7]
	v_mfma_f32_16x16x32_bf16 v[32:35], v[208:211], v[176:179], v[32:35]
	v_mfma_f32_16x16x32_bf16 v[28:31], v[234:237], v[176:179], v[28:31]
	v_mfma_f32_16x16x32_bf16 v[24:27], v[208:211], v[184:187], v[24:27]
	v_mfma_f32_16x16x32_bf16 v[20:23], v[234:237], v[184:187], v[20:23]
	v_mfma_f32_16x16x32_bf16 v[16:19], v[208:211], v[192:195], v[16:19]
	v_mfma_f32_16x16x32_bf16 v[12:15], v[234:237], v[192:195], v[12:15]
	v_mfma_f32_16x16x32_bf16 v[8:11], v[208:211], v[200:203], v[8:11]
	v_mfma_f32_16x16x32_bf16 v[4:7], v[234:237], v[200:203], v[4:7]
	s_add_i32 s45, 0, 0x18000
	v_add_u32_e32 v147, s45, v141
	s_barrier
	ds_read_b128 v[148:151], v147
	ds_read_b128 v[152:155], v147 offset:1024
	ds_read_b128 v[156:159], v147 offset:2048
	ds_read_b128 v[160:163], v147 offset:3072
	s_add_u32 s16, s16, 0x40000
	s_addc_u32 s17, s17, 0
	s_mov_b32 m0, s27
	v_lshl_add_u64 v[204:205], s[16:17], 0, v[134:135]
	ds_read_b128 v[172:175], v146 offset:32768
	ds_read_b128 v[176:179], v146 offset:33792
	ds_read_b128 v[180:183], v146 offset:34816
	ds_read_b128 v[184:187], v146 offset:35840
	ds_read_b128 v[188:191], v146 offset:36864
	ds_read_b128 v[192:195], v146 offset:37888
	ds_read_b128 v[196:199], v146 offset:38912
	ds_read_b128 v[200:203], v146 offset:39936
	global_load_lds_dwordx4 v[204:205], off
	v_lshl_add_u64 v[204:205], s[16:17], 0, v[132:133]
	s_mov_b32 m0, s30
	s_nop 0
	global_load_lds_dwordx4 v[204:205], off
	s_waitcnt lgkmcnt(8)
	s_barrier
	s_waitcnt lgkmcnt(0)
	s_waitcnt lgkmcnt(0)
	v_mfma_f32_16x16x32_bf16 v[128:131], v[148:151], v[172:175], v[128:131]
	v_mfma_f32_16x16x32_bf16 v[124:127], v[156:159], v[172:175], v[124:127]
	v_mfma_f32_16x16x32_bf16 v[120:123], v[148:151], v[180:183], v[120:123]
	v_mfma_f32_16x16x32_bf16 v[116:119], v[156:159], v[180:183], v[116:119]
	v_mfma_f32_16x16x32_bf16 v[112:115], v[148:151], v[188:191], v[112:115]
	v_mfma_f32_16x16x32_bf16 v[108:111], v[156:159], v[188:191], v[108:111]
	v_mfma_f32_16x16x32_bf16 v[104:107], v[148:151], v[196:199], v[104:107]
	v_mfma_f32_16x16x32_bf16 v[100:103], v[156:159], v[196:199], v[100:103]
	v_mfma_f32_16x16x32_bf16 v[128:131], v[152:155], v[176:179], v[128:131]
	v_mfma_f32_16x16x32_bf16 v[124:127], v[160:163], v[176:179], v[124:127]
	v_mfma_f32_16x16x32_bf16 v[120:123], v[152:155], v[184:187], v[120:123]
	v_mfma_f32_16x16x32_bf16 v[116:119], v[160:163], v[184:187], v[116:119]
	v_mfma_f32_16x16x32_bf16 v[112:115], v[152:155], v[192:195], v[112:115]
	v_mfma_f32_16x16x32_bf16 v[108:111], v[160:163], v[192:195], v[108:111]
	v_mfma_f32_16x16x32_bf16 v[104:107], v[152:155], v[200:203], v[104:107]
	v_mfma_f32_16x16x32_bf16 v[100:103], v[160:163], v[200:203], v[100:103]
	s_barrier
	s_add_i32 s48, 0, 0x1c000
	s_add_i32 s16, s45, s22
	v_add_u32_e32 v147, s48, v141
	v_lshl_add_u64 v[168:169], v[168:169], 0, s[28:29]
	s_mov_b32 m0, s16
	ds_read_b128 v[204:207], v147
	ds_read_b128 v[208:211], v147 offset:1024
	ds_read_b128 v[220:223], v147 offset:2048
	ds_read_b128 v[234:237], v147 offset:3072
	global_load_lds_dwordx4 v[168:169], off
	v_lshl_add_u64 v[168:169], v[214:215], 0, s[28:29]
	s_add_i32 m0, s16, 0x2000
	s_nop 0
	global_load_lds_dwordx4 v[168:169], off
	s_barrier
	s_waitcnt lgkmcnt(0)
	s_waitcnt lgkmcnt(0)
	v_mfma_f32_16x16x32_bf16 v[84:87], v[204:207], v[172:175], v[84:87]
	v_mfma_f32_16x16x32_bf16 v[76:79], v[220:223], v[172:175], v[76:79]
	v_mfma_f32_16x16x32_bf16 v[72:75], v[204:207], v[180:183], v[72:75]
	v_mfma_f32_16x16x32_bf16 v[68:71], v[220:223], v[180:183], v[68:71]
	v_mfma_f32_16x16x32_bf16 v[56:59], v[204:207], v[188:191], v[56:59]
	v_mfma_f32_16x16x32_bf16 v[52:55], v[220:223], v[188:191], v[52:55]
	v_mfma_f32_16x16x32_bf16 v[44:47], v[204:207], v[196:199], v[44:47]
	v_mfma_f32_16x16x32_bf16 v[36:39], v[220:223], v[196:199], v[36:39]
	v_mfma_f32_16x16x32_bf16 v[84:87], v[208:211], v[176:179], v[84:87]
	v_mfma_f32_16x16x32_bf16 v[76:79], v[234:237], v[176:179], v[76:79]
	v_mfma_f32_16x16x32_bf16 v[72:75], v[208:211], v[184:187], v[72:75]
	v_mfma_f32_16x16x32_bf16 v[68:71], v[234:237], v[184:187], v[68:71]
	v_mfma_f32_16x16x32_bf16 v[56:59], v[208:211], v[192:195], v[56:59]
	v_mfma_f32_16x16x32_bf16 v[52:55], v[234:237], v[192:195], v[52:55]
	v_mfma_f32_16x16x32_bf16 v[44:47], v[208:211], v[200:203], v[44:47]
	v_mfma_f32_16x16x32_bf16 v[36:39], v[234:237], v[200:203], v[36:39]
	s_mov_b32 m0, s31
	v_lshl_add_u64 v[168:169], v[224:225], 0, s[28:29]
	s_barrier
	ds_read_b128 v[172:175], v146 offset:49152
	ds_read_b128 v[176:179], v146 offset:50176
	ds_read_b128 v[180:183], v146 offset:51200
	ds_read_b128 v[184:187], v146 offset:52224
	ds_read_b128 v[188:191], v146 offset:53248
	ds_read_b128 v[192:195], v146 offset:54272
	ds_read_b128 v[196:199], v146 offset:55296
	ds_read_b128 v[200:203], v146 offset:56320
	global_load_lds_dwordx4 v[168:169], off
	v_lshl_add_u64 v[168:169], v[238:239], 0, s[28:29]
	s_mov_b32 m0, s36
	s_nop 0
	global_load_lds_dwordx4 v[168:169], off
	s_barrier
	s_waitcnt lgkmcnt(0)
	s_waitcnt lgkmcnt(0)
	v_mfma_f32_16x16x32_bf16 v[96:99], v[148:151], v[172:175], v[96:99]
	v_mfma_f32_16x16x32_bf16 v[92:95], v[156:159], v[172:175], v[92:95]
	v_mfma_f32_16x16x32_bf16 v[88:91], v[148:151], v[180:183], v[88:91]
	v_mfma_f32_16x16x32_bf16 v[80:83], v[156:159], v[180:183], v[80:83]
	v_mfma_f32_16x16x32_bf16 v[64:67], v[148:151], v[188:191], v[64:67]
	v_mfma_f32_16x16x32_bf16 v[60:63], v[156:159], v[188:191], v[60:63]
	v_mfma_f32_16x16x32_bf16 v[48:51], v[148:151], v[196:199], v[48:51]
	v_mfma_f32_16x16x32_bf16 v[40:43], v[156:159], v[196:199], v[40:43]
	v_mfma_f32_16x16x32_bf16 v[96:99], v[152:155], v[176:179], v[96:99]
	v_mfma_f32_16x16x32_bf16 v[92:95], v[160:163], v[176:179], v[92:95]
	v_mfma_f32_16x16x32_bf16 v[88:91], v[152:155], v[184:187], v[88:91]
	v_mfma_f32_16x16x32_bf16 v[80:83], v[160:163], v[184:187], v[80:83]
	v_mfma_f32_16x16x32_bf16 v[64:67], v[152:155], v[192:195], v[64:67]
	v_mfma_f32_16x16x32_bf16 v[60:63], v[160:163], v[192:195], v[60:63]
	v_mfma_f32_16x16x32_bf16 v[48:51], v[152:155], v[200:203], v[48:51]
	v_mfma_f32_16x16x32_bf16 v[40:43], v[160:163], v[200:203], v[40:43]
	s_barrier
	s_add_u32 s16, s20, 0x40080
	s_addc_u32 s17, s21, 0
	s_add_i32 s20, s48, s22
	v_lshl_add_u64 v[148:149], s[16:17], 0, v[2:3]
	s_mov_b32 m0, s20
	s_nop 0
	global_load_lds_dwordx4 v[148:149], off
	v_lshl_add_u64 v[148:149], s[16:17], 0, v[0:1]
	s_add_i32 m0, s20, 0x2000
	s_nop 0
	global_load_lds_dwordx4 v[148:149], off
	s_waitcnt vmcnt(6)
	s_barrier
	v_mfma_f32_16x16x32_bf16 v[32:35], v[204:207], v[172:175], v[32:35]
	v_mfma_f32_16x16x32_bf16 v[28:31], v[220:223], v[172:175], v[28:31]
	v_mfma_f32_16x16x32_bf16 v[24:27], v[204:207], v[180:183], v[24:27]
	v_mfma_f32_16x16x32_bf16 v[20:23], v[220:223], v[180:183], v[20:23]
	v_mfma_f32_16x16x32_bf16 v[16:19], v[204:207], v[188:191], v[16:19]
	v_mfma_f32_16x16x32_bf16 v[12:15], v[220:223], v[188:191], v[12:15]
	v_mfma_f32_16x16x32_bf16 v[8:11], v[204:207], v[196:199], v[8:11]
	v_mfma_f32_16x16x32_bf16 v[4:7], v[220:223], v[196:199], v[4:7]
	v_mfma_f32_16x16x32_bf16 v[32:35], v[208:211], v[176:179], v[32:35]
	v_mfma_f32_16x16x32_bf16 v[28:31], v[234:237], v[176:179], v[28:31]
	v_mfma_f32_16x16x32_bf16 v[24:27], v[208:211], v[184:187], v[24:27]
	v_mfma_f32_16x16x32_bf16 v[20:23], v[234:237], v[184:187], v[20:23]
	v_mfma_f32_16x16x32_bf16 v[16:19], v[208:211], v[192:195], v[16:19]
	v_mfma_f32_16x16x32_bf16 v[12:15], v[234:237], v[192:195], v[12:15]
	v_mfma_f32_16x16x32_bf16 v[8:11], v[208:211], v[200:203], v[8:11]
	v_mfma_f32_16x16x32_bf16 v[4:7], v[234:237], v[200:203], v[4:7]
	s_add_i32 s44, s44, 2
	s_add_u32 s10, s10, 0x100
	s_addc_u32 s11, s11, 0
	s_add_u32 s1, s1, 0x100
	s_addc_u32 s3, s3, 0
	s_cmp_gt_u32 s44, 13
	s_barrier
	s_cbranch_scc0 .LBB0_840
	s_lshl_b32 s1, s47, 8
	v_add_u32_e32 v148, s1, v140
	v_lshl_or_b32 v150, s46, 8, v145
	v_ashrrev_i32_e32 v149, 31, v148
	v_cvt_pk_bf16_f32 v128, v128, v129
	v_cvt_pk_bf16_f32 v129, v130, v131
	v_cvt_pk_bf16_f32 v130, v124, v125
	v_add_u32_e32 v124, s1, v142
	v_lshlrev_b64 v[152:153], 11, v[148:149]
	v_ashrrev_i32_e32 v151, 31, v150
	v_ashrrev_i32_e32 v125, 31, v124
	v_cvt_pk_bf16_f32 v120, v120, v121
	v_cvt_pk_bf16_f32 v121, v122, v123
	v_cvt_pk_bf16_f32 v122, v116, v117
	v_add_u32_e32 v116, s1, v143
	v_lshl_add_u64 v[152:153], s[82:83], 0, v[152:153]
	v_lshlrev_b64 v[150:151], 1, v[150:151]
	v_lshlrev_b64 v[124:125], 11, v[124:125]
	v_ashrrev_i32_e32 v117, 31, v116
	v_cvt_pk_bf16_f32 v112, v112, v113
	v_cvt_pk_bf16_f32 v113, v114, v115
	v_cvt_pk_bf16_f32 v114, v108, v109
	v_add_u32_e32 v108, s1, v144
	v_cvt_pk_bf16_f32 v104, v104, v105
	v_cvt_pk_bf16_f32 v105, v106, v107
	v_cvt_pk_bf16_f32 v106, v100, v101
	v_add_u32_e32 v100, 0x80, v148
	v_cvt_pk_bf16_f32 v96, v96, v97
	v_cvt_pk_bf16_f32 v97, v98, v99
	v_cvt_pk_bf16_f32 v98, v92, v93
	v_add_u32_e32 v92, 0x90, v148
	v_cvt_pk_bf16_f32 v88, v88, v89
	v_cvt_pk_bf16_f32 v89, v90, v91
	v_cvt_pk_bf16_f32 v90, v80, v81
	v_add_u32_e32 v80, 0xa0, v148
	v_cvt_pk_bf16_f32 v64, v64, v65
	v_cvt_pk_bf16_f32 v65, v66, v67
	v_cvt_pk_bf16_f32 v66, v60, v61
	v_add_u32_e32 v60, 0xb0, v148
	v_lshl_add_u64 v[152:153], v[152:153], 0, v[150:151]
	v_lshl_add_u64 v[124:125], s[82:83], 0, v[124:125]
	v_lshlrev_b64 v[116:117], 11, v[116:117]
	v_ashrrev_i32_e32 v109, 31, v108
	v_ashrrev_i32_e32 v101, 31, v100
	v_ashrrev_i32_e32 v93, 31, v92
	v_ashrrev_i32_e32 v81, 31, v80
	v_ashrrev_i32_e32 v61, 31, v60
	v_cvt_pk_bf16_f32 v48, v48, v49
	v_cvt_pk_bf16_f32 v49, v50, v51
	v_cvt_pk_bf16_f32 v50, v40, v41
	v_cvt_pk_bf16_f32 v51, v42, v43
	v_cvt_pk_bf16_f32 v40, v84, v85
	v_cvt_pk_bf16_f32 v41, v86, v87
	v_cvt_pk_bf16_f32 v42, v76, v77
	v_cvt_pk_bf16_f32 v43, v78, v79
	v_lshl_add_u64 v[124:125], v[124:125], 0, v[150:151]
	v_lshl_add_u64 v[116:117], s[82:83], 0, v[116:117]
	v_lshlrev_b64 v[108:109], 11, v[108:109]
	v_lshlrev_b64 v[100:101], 11, v[100:101]
	v_lshlrev_b64 v[92:93], 11, v[92:93]
	v_lshlrev_b64 v[80:81], 11, v[80:81]
	v_lshlrev_b64 v[60:61], 11, v[60:61]
	global_store_dwordx4 v[152:153], v[40:43], off offset:256
	v_lshl_add_u64 v[116:117], v[116:117], 0, v[150:151]
	v_lshl_add_u64 v[108:109], s[82:83], 0, v[108:109]
	v_cvt_pk_bf16_f32 v40, v72, v73
	v_cvt_pk_bf16_f32 v41, v74, v75
	v_cvt_pk_bf16_f32 v42, v68, v69
	v_cvt_pk_bf16_f32 v43, v70, v71
	v_lshl_add_u64 v[100:101], s[82:83], 0, v[100:101]
	v_lshl_add_u64 v[92:93], s[82:83], 0, v[92:93]
	v_lshl_add_u64 v[80:81], s[82:83], 0, v[80:81]
	v_lshl_add_u64 v[60:61], s[82:83], 0, v[60:61]
	global_store_dwordx4 v[124:125], v[40:43], off offset:256
	v_cvt_pk_bf16_f32 v131, v126, v127
	v_cvt_pk_bf16_f32 v123, v118, v119
	v_cvt_pk_bf16_f32 v40, v56, v57
	v_cvt_pk_bf16_f32 v41, v58, v59
	v_cvt_pk_bf16_f32 v42, v52, v53
	v_cvt_pk_bf16_f32 v43, v54, v55
	v_cvt_pk_bf16_f32 v115, v110, v111
	v_lshl_add_u64 v[108:109], v[108:109], 0, v[150:151]
	v_cvt_pk_bf16_f32 v107, v102, v103
	v_lshl_add_u64 v[100:101], v[100:101], 0, v[150:151]
	v_cvt_pk_bf16_f32 v99, v94, v95
	v_lshl_add_u64 v[92:93], v[92:93], 0, v[150:151]
	v_cvt_pk_bf16_f32 v91, v82, v83
	v_lshl_add_u64 v[80:81], v[80:81], 0, v[150:151]
	v_cvt_pk_bf16_f32 v67, v62, v63
	v_lshl_add_u64 v[60:61], v[60:61], 0, v[150:151]
	global_store_dwordx4 v[116:117], v[40:43], off offset:256
	v_cvt_pk_bf16_f32 v32, v32, v33
	v_cvt_pk_bf16_f32 v33, v34, v35
	v_cvt_pk_bf16_f32 v40, v44, v45
	v_cvt_pk_bf16_f32 v41, v46, v47
	v_cvt_pk_bf16_f32 v42, v36, v37
	v_cvt_pk_bf16_f32 v43, v38, v39
	v_cvt_pk_bf16_f32 v34, v28, v29
	v_cvt_pk_bf16_f32 v35, v30, v31
	v_cvt_pk_bf16_f32 v24, v24, v25
	v_cvt_pk_bf16_f32 v25, v26, v27
	v_cvt_pk_bf16_f32 v26, v20, v21
	v_cvt_pk_bf16_f32 v27, v22, v23
	v_cvt_pk_bf16_f32 v16, v16, v17
	v_cvt_pk_bf16_f32 v17, v18, v19
	v_cvt_pk_bf16_f32 v18, v12, v13
	v_cvt_pk_bf16_f32 v19, v14, v15
	v_cvt_pk_bf16_f32 v8, v8, v9
	v_cvt_pk_bf16_f32 v9, v10, v11
	v_cvt_pk_bf16_f32 v10, v4, v5
	v_cvt_pk_bf16_f32 v11, v6, v7
	s_and_b64 vcc, exec, s[42:43]
	s_mov_b32 s46, s0
	s_mov_b32 s47, s2
	s_mov_b64 s[16:17], s[8:9]
	s_mov_b64 s[10:11], s[4:5]
	s_mov_b64 s[48:49], 0x5201400
	global_store_dwordx4 v[152:153], v[128:131], off
	global_store_dwordx4 v[124:125], v[120:123], off
	global_store_dwordx4 v[116:117], v[112:115], off
	global_store_dwordx4 v[108:109], v[104:107], off
	global_store_dwordx4 v[100:101], v[96:99], off
	global_store_dwordx4 v[92:93], v[88:91], off
	global_store_dwordx4 v[80:81], v[64:67], off
	global_store_dwordx4 v[60:61], v[48:51], off
	global_store_dwordx4 v[108:109], v[40:43], off offset:256
	global_store_dwordx4 v[100:101], v[32:35], off offset:256
	global_store_dwordx4 v[92:93], v[24:27], off offset:256
	global_store_dwordx4 v[80:81], v[16:19], off offset:256
	global_store_dwordx4 v[60:61], v[8:11], off offset:256
	s_cbranch_vccz .LBB0_831
	s_waitcnt vmcnt(0)
	s_cmpk_gt_u32 s18, 0xff
	v_readlane_b32 s36, v254, 31
	v_readlane_b32 s37, v254, 32
	s_cbranch_scc1 .LBB0_844
	s_barrier

.LBB0_1098:
	s_add_u32 s4, s2, 0xfffc0080
	s_addc_u32 s5, s3, -1
	s_add_i32 s72, 0, 0x10000
	v_add_u32_e32 v152, s72, v157
	ds_read_b128 v[140:143], v152
	ds_read_b128 v[144:147], v152 offset:1024
	ds_read_b128 v[148:151], v152 offset:2048
	ds_read_b128 v[152:155], v152 offset:3072
	s_cmp_eq_u32 s53, 12
	s_cselect_b32 s17, s49, s5
	s_cselect_b32 s16, s48, s4
	s_cselect_b32 s5, s21, s11
	s_cselect_b32 s4, s20, s9
	v_lshl_add_u64 v[168:169], s[2:3], 0, v[136:137]
	s_add_i32 m0, s26, 0xc000
	ds_read_b128 v[160:163], v159
	ds_read_b128 v[172:175], v159 offset:1024
	ds_read_b128 v[176:179], v159 offset:2048
	ds_read_b128 v[180:183], v159 offset:3072
	ds_read_b128 v[184:187], v159 offset:4096
	ds_read_b128 v[188:191], v159 offset:5120
	ds_read_b128 v[192:195], v159 offset:6144
	ds_read_b128 v[196:199], v159 offset:7168
	global_load_lds_dwordx4 v[168:169], off
	v_lshl_add_u64 v[168:169], s[2:3], 0, v[138:139]
	s_add_i32 m0, s26, 0xe000
	s_nop 0
	global_load_lds_dwordx4 v[168:169], off
	s_waitcnt lgkmcnt(8)
	s_barrier
	s_waitcnt lgkmcnt(0)
	s_waitcnt lgkmcnt(0)
	v_mfma_f32_16x16x32_bf16 v[128:131], v[140:143], v[160:163], v[128:131]
	v_mfma_f32_16x16x32_bf16 v[124:127], v[148:151], v[160:163], v[124:127]
	v_mfma_f32_16x16x32_bf16 v[120:123], v[140:143], v[176:179], v[120:123]
	v_mfma_f32_16x16x32_bf16 v[116:119], v[148:151], v[176:179], v[116:119]
	v_mfma_f32_16x16x32_bf16 v[112:115], v[140:143], v[184:187], v[112:115]
	v_mfma_f32_16x16x32_bf16 v[108:111], v[148:151], v[184:187], v[108:111]
	v_mfma_f32_16x16x32_bf16 v[104:107], v[140:143], v[192:195], v[104:107]
	v_mfma_f32_16x16x32_bf16 v[100:103], v[148:151], v[192:195], v[100:103]
	v_mfma_f32_16x16x32_bf16 v[128:131], v[144:147], v[172:175], v[128:131]
	v_mfma_f32_16x16x32_bf16 v[124:127], v[152:155], v[172:175], v[124:127]
	v_mfma_f32_16x16x32_bf16 v[120:123], v[144:147], v[180:183], v[120:123]
	v_mfma_f32_16x16x32_bf16 v[116:119], v[152:155], v[180:183], v[116:119]
	v_mfma_f32_16x16x32_bf16 v[112:115], v[144:147], v[188:191], v[112:115]
	v_mfma_f32_16x16x32_bf16 v[108:111], v[152:155], v[188:191], v[108:111]
	v_mfma_f32_16x16x32_bf16 v[104:107], v[144:147], v[196:199], v[104:107]
	v_mfma_f32_16x16x32_bf16 v[100:103], v[152:155], v[196:199], v[100:103]
	s_barrier
	s_add_i32 s74, 0, 0x14000
	v_add_u32_e32 v168, s74, v157
	s_add_i32 s72, s72, s23
	ds_read_b128 v[200:203], v168
	ds_read_b128 v[204:207], v168 offset:1024
	ds_read_b128 v[208:211], v168 offset:2048
	ds_read_b128 v[220:223], v168 offset:3072
	v_lshl_add_u64 v[168:169], s[4:5], 0, v[2:3]
	s_mov_b32 m0, s72
	v_lshl_add_u64 v[214:215], s[4:5], 0, v[0:1]
	global_load_lds_dwordx4 v[168:169], off
	s_add_i32 m0, s72, 0x2000
	s_nop 0
	global_load_lds_dwordx4 v[214:215], off
	s_barrier
	s_waitcnt lgkmcnt(0)
	s_waitcnt lgkmcnt(0)
	v_mfma_f32_16x16x32_bf16 v[72:75], v[200:203], v[160:163], v[72:75]
	v_mfma_f32_16x16x32_bf16 v[68:71], v[208:211], v[160:163], v[68:71]
	v_mfma_f32_16x16x32_bf16 v[56:59], v[200:203], v[176:179], v[56:59]
	v_mfma_f32_16x16x32_bf16 v[52:55], v[208:211], v[176:179], v[52:55]
	v_mfma_f32_16x16x32_bf16 v[48:51], v[200:203], v[184:187], v[48:51]
	v_mfma_f32_16x16x32_bf16 v[44:47], v[208:211], v[184:187], v[44:47]
	v_mfma_f32_16x16x32_bf16 v[40:43], v[200:203], v[192:195], v[40:43]
	v_mfma_f32_16x16x32_bf16 v[36:39], v[208:211], v[192:195], v[36:39]
	v_mfma_f32_16x16x32_bf16 v[72:75], v[204:207], v[172:175], v[72:75]
	v_mfma_f32_16x16x32_bf16 v[68:71], v[220:223], v[172:175], v[68:71]
	v_mfma_f32_16x16x32_bf16 v[56:59], v[204:207], v[180:183], v[56:59]
	v_mfma_f32_16x16x32_bf16 v[52:55], v[220:223], v[180:183], v[52:55]
	v_mfma_f32_16x16x32_bf16 v[48:51], v[204:207], v[188:191], v[48:51]
	v_mfma_f32_16x16x32_bf16 v[44:47], v[220:223], v[188:191], v[44:47]
	v_mfma_f32_16x16x32_bf16 v[40:43], v[204:207], v[196:199], v[40:43]
	v_mfma_f32_16x16x32_bf16 v[36:39], v[220:223], v[196:199], v[36:39]
	s_mov_b32 m0, s26
	v_lshl_add_u64 v[224:225], s[16:17], 0, v[134:135]
	s_barrier
	ds_read_b128 v[160:163], v159 offset:16384
	ds_read_b128 v[172:175], v159 offset:17408
	ds_read_b128 v[176:179], v159 offset:18432
	ds_read_b128 v[180:183], v159 offset:19456
	ds_read_b128 v[184:187], v159 offset:20480
	ds_read_b128 v[188:191], v159 offset:21504
	ds_read_b128 v[192:195], v159 offset:22528
	ds_read_b128 v[196:199], v159 offset:23552
	global_load_lds_dwordx4 v[224:225], off
	v_lshl_add_u64 v[234:235], s[16:17], 0, v[132:133]
	s_mov_b32 m0, s27
	s_nop 0
	global_load_lds_dwordx4 v[234:235], off
	s_barrier
	s_waitcnt lgkmcnt(0)
	s_waitcnt lgkmcnt(0)
	v_mfma_f32_16x16x32_bf16 v[96:99], v[140:143], v[160:163], v[96:99]
	v_mfma_f32_16x16x32_bf16 v[92:95], v[148:151], v[160:163], v[92:95]
	v_mfma_f32_16x16x32_bf16 v[88:91], v[140:143], v[176:179], v[88:91]
	v_mfma_f32_16x16x32_bf16 v[84:87], v[148:151], v[176:179], v[84:87]
	v_mfma_f32_16x16x32_bf16 v[80:83], v[140:143], v[184:187], v[80:83]
	v_mfma_f32_16x16x32_bf16 v[76:79], v[148:151], v[184:187], v[76:79]
	v_mfma_f32_16x16x32_bf16 v[64:67], v[140:143], v[192:195], v[64:67]
	v_mfma_f32_16x16x32_bf16 v[60:63], v[148:151], v[192:195], v[60:63]
	v_mfma_f32_16x16x32_bf16 v[96:99], v[144:147], v[172:175], v[96:99]
	v_mfma_f32_16x16x32_bf16 v[92:95], v[152:155], v[172:175], v[92:95]
	v_mfma_f32_16x16x32_bf16 v[88:91], v[144:147], v[180:183], v[88:91]
	v_mfma_f32_16x16x32_bf16 v[84:87], v[152:155], v[180:183], v[84:87]
	v_mfma_f32_16x16x32_bf16 v[80:83], v[144:147], v[188:191], v[80:83]
	v_mfma_f32_16x16x32_bf16 v[76:79], v[152:155], v[188:191], v[76:79]
	v_mfma_f32_16x16x32_bf16 v[64:67], v[144:147], v[196:199], v[64:67]
	v_mfma_f32_16x16x32_bf16 v[60:63], v[152:155], v[196:199], v[60:63]
	s_barrier
	s_add_u32 s72, s4, 0x40000
	s_addc_u32 s73, s5, 0
	s_add_i32 s74, s74, s23
	v_lshl_add_u64 v[140:141], s[72:73], 0, v[2:3]
	s_mov_b32 m0, s74
	s_nop 0
	global_load_lds_dwordx4 v[140:141], off
	v_lshl_add_u64 v[140:141], s[72:73], 0, v[0:1]
	s_add_i32 m0, s74, 0x2000
	s_nop 0
	global_load_lds_dwordx4 v[140:141], off
	s_waitcnt vmcnt(6)
	s_barrier
	v_mfma_f32_16x16x32_bf16 v[32:35], v[200:203], v[160:163], v[32:35]
	v_mfma_f32_16x16x32_bf16 v[28:31], v[208:211], v[160:163], v[28:31]
	v_mfma_f32_16x16x32_bf16 v[24:27], v[200:203], v[176:179], v[24:27]
	v_mfma_f32_16x16x32_bf16 v[20:23], v[208:211], v[176:179], v[20:23]
	v_mfma_f32_16x16x32_bf16 v[16:19], v[200:203], v[184:187], v[16:19]
	v_mfma_f32_16x16x32_bf16 v[12:15], v[208:211], v[184:187], v[12:15]
	v_mfma_f32_16x16x32_bf16 v[8:11], v[200:203], v[192:195], v[8:11]
	v_mfma_f32_16x16x32_bf16 v[4:7], v[208:211], v[192:195], v[4:7]
	v_mfma_f32_16x16x32_bf16 v[32:35], v[204:207], v[172:175], v[32:35]
	v_mfma_f32_16x16x32_bf16 v[28:31], v[220:223], v[172:175], v[28:31]
	v_mfma_f32_16x16x32_bf16 v[24:27], v[204:207], v[180:183], v[24:27]
	v_mfma_f32_16x16x32_bf16 v[20:23], v[220:223], v[180:183], v[20:23]
	v_mfma_f32_16x16x32_bf16 v[16:19], v[204:207], v[188:191], v[16:19]
	v_mfma_f32_16x16x32_bf16 v[12:15], v[220:223], v[188:191], v[12:15]
	v_mfma_f32_16x16x32_bf16 v[8:11], v[204:207], v[196:199], v[8:11]
	v_mfma_f32_16x16x32_bf16 v[4:7], v[220:223], v[196:199], v[4:7]
	s_add_i32 s72, 0, 0x18000
	v_add_u32_e32 v152, s72, v157
	s_barrier
	ds_read_b128 v[140:143], v152
	ds_read_b128 v[144:147], v152 offset:1024
	ds_read_b128 v[148:151], v152 offset:2048
	ds_read_b128 v[152:155], v152 offset:3072
	s_add_u32 s16, s16, 0x40000
	s_addc_u32 s17, s17, 0
	s_mov_b32 m0, s30
	v_lshl_add_u64 v[200:201], s[16:17], 0, v[134:135]
	ds_read_b128 v[160:163], v159 offset:32768
	ds_read_b128 v[172:175], v159 offset:33792
	ds_read_b128 v[176:179], v159 offset:34816
	ds_read_b128 v[180:183], v159 offset:35840
	ds_read_b128 v[184:187], v159 offset:36864
	ds_read_b128 v[188:191], v159 offset:37888
	ds_read_b128 v[192:195], v159 offset:38912
	ds_read_b128 v[196:199], v159 offset:39936
	global_load_lds_dwordx4 v[200:201], off
	v_lshl_add_u64 v[200:201], s[16:17], 0, v[132:133]
	s_mov_b32 m0, s31
	s_nop 0
	global_load_lds_dwordx4 v[200:201], off
	s_waitcnt lgkmcnt(8)
	s_barrier
	s_waitcnt lgkmcnt(0)
	s_waitcnt lgkmcnt(0)
	v_mfma_f32_16x16x32_bf16 v[128:131], v[140:143], v[160:163], v[128:131]
	v_mfma_f32_16x16x32_bf16 v[124:127], v[148:151], v[160:163], v[124:127]
	v_mfma_f32_16x16x32_bf16 v[120:123], v[140:143], v[176:179], v[120:123]
	v_mfma_f32_16x16x32_bf16 v[116:119], v[148:151], v[176:179], v[116:119]
	v_mfma_f32_16x16x32_bf16 v[112:115], v[140:143], v[184:187], v[112:115]
	v_mfma_f32_16x16x32_bf16 v[108:111], v[148:151], v[184:187], v[108:111]
	v_mfma_f32_16x16x32_bf16 v[104:107], v[140:143], v[192:195], v[104:107]
	v_mfma_f32_16x16x32_bf16 v[100:103], v[148:151], v[192:195], v[100:103]
	v_mfma_f32_16x16x32_bf16 v[128:131], v[144:147], v[172:175], v[128:131]
	v_mfma_f32_16x16x32_bf16 v[124:127], v[152:155], v[172:175], v[124:127]
	v_mfma_f32_16x16x32_bf16 v[120:123], v[144:147], v[180:183], v[120:123]
	v_mfma_f32_16x16x32_bf16 v[116:119], v[152:155], v[180:183], v[116:119]
	v_mfma_f32_16x16x32_bf16 v[112:115], v[144:147], v[188:191], v[112:115]
	v_mfma_f32_16x16x32_bf16 v[108:111], v[152:155], v[188:191], v[108:111]
	v_mfma_f32_16x16x32_bf16 v[104:107], v[144:147], v[196:199], v[104:107]
	v_mfma_f32_16x16x32_bf16 v[100:103], v[152:155], v[196:199], v[100:103]
	s_barrier
	s_add_i32 s16, 0, 0x1c000
	s_add_i32 s17, s72, s23
	v_add_u32_e32 v170, s16, v157
	v_lshl_add_u64 v[168:169], v[168:169], 0, s[28:29]
	s_mov_b32 m0, s17
	ds_read_b128 v[200:203], v170
	ds_read_b128 v[204:207], v170 offset:1024
	ds_read_b128 v[208:211], v170 offset:2048
	ds_read_b128 v[220:223], v170 offset:3072
	global_load_lds_dwordx4 v[168:169], off
	v_lshl_add_u64 v[168:169], v[214:215], 0, s[28:29]
	s_add_i32 m0, s17, 0x2000
	s_nop 0
	global_load_lds_dwordx4 v[168:169], off
	s_barrier
	s_waitcnt lgkmcnt(0)
	s_waitcnt lgkmcnt(0)
	v_mfma_f32_16x16x32_bf16 v[72:75], v[200:203], v[160:163], v[72:75]
	v_mfma_f32_16x16x32_bf16 v[68:71], v[208:211], v[160:163], v[68:71]
	v_mfma_f32_16x16x32_bf16 v[56:59], v[200:203], v[176:179], v[56:59]
	v_mfma_f32_16x16x32_bf16 v[52:55], v[208:211], v[176:179], v[52:55]
	v_mfma_f32_16x16x32_bf16 v[48:51], v[200:203], v[184:187], v[48:51]
	v_mfma_f32_16x16x32_bf16 v[44:47], v[208:211], v[184:187], v[44:47]
	v_mfma_f32_16x16x32_bf16 v[40:43], v[200:203], v[192:195], v[40:43]
	v_mfma_f32_16x16x32_bf16 v[36:39], v[208:211], v[192:195], v[36:39]
	v_mfma_f32_16x16x32_bf16 v[72:75], v[204:207], v[172:175], v[72:75]
	v_mfma_f32_16x16x32_bf16 v[68:71], v[220:223], v[172:175], v[68:71]
	v_mfma_f32_16x16x32_bf16 v[56:59], v[204:207], v[180:183], v[56:59]
	v_mfma_f32_16x16x32_bf16 v[52:55], v[220:223], v[180:183], v[52:55]
	v_mfma_f32_16x16x32_bf16 v[48:51], v[204:207], v[188:191], v[48:51]
	v_mfma_f32_16x16x32_bf16 v[44:47], v[220:223], v[188:191], v[44:47]
	v_mfma_f32_16x16x32_bf16 v[40:43], v[204:207], v[196:199], v[40:43]
	v_mfma_f32_16x16x32_bf16 v[36:39], v[220:223], v[196:199], v[36:39]
	s_mov_b32 m0, s50
	v_lshl_add_u64 v[168:169], v[224:225], 0, s[28:29]
	s_barrier
	ds_read_b128 v[160:163], v159 offset:49152
	ds_read_b128 v[172:175], v159 offset:50176
	ds_read_b128 v[176:179], v159 offset:51200
	ds_read_b128 v[180:183], v159 offset:52224
	ds_read_b128 v[184:187], v159 offset:53248
	ds_read_b128 v[188:191], v159 offset:54272
	ds_read_b128 v[192:195], v159 offset:55296
	ds_read_b128 v[196:199], v159 offset:56320
	global_load_lds_dwordx4 v[168:169], off
	v_lshl_add_u64 v[168:169], v[234:235], 0, s[28:29]
	s_mov_b32 m0, s51
	s_nop 0
	global_load_lds_dwordx4 v[168:169], off
	s_barrier
	s_waitcnt lgkmcnt(0)
	s_waitcnt lgkmcnt(0)
	v_mfma_f32_16x16x32_bf16 v[96:99], v[140:143], v[160:163], v[96:99]
	v_mfma_f32_16x16x32_bf16 v[92:95], v[148:151], v[160:163], v[92:95]
	v_mfma_f32_16x16x32_bf16 v[88:91], v[140:143], v[176:179], v[88:91]
	v_mfma_f32_16x16x32_bf16 v[84:87], v[148:151], v[176:179], v[84:87]
	v_mfma_f32_16x16x32_bf16 v[80:83], v[140:143], v[184:187], v[80:83]
	v_mfma_f32_16x16x32_bf16 v[76:79], v[148:151], v[184:187], v[76:79]
	v_mfma_f32_16x16x32_bf16 v[64:67], v[140:143], v[192:195], v[64:67]
	v_mfma_f32_16x16x32_bf16 v[60:63], v[148:151], v[192:195], v[60:63]
	v_mfma_f32_16x16x32_bf16 v[96:99], v[144:147], v[172:175], v[96:99]
	v_mfma_f32_16x16x32_bf16 v[92:95], v[152:155], v[172:175], v[92:95]
	v_mfma_f32_16x16x32_bf16 v[88:91], v[144:147], v[180:183], v[88:91]
	v_mfma_f32_16x16x32_bf16 v[84:87], v[152:155], v[180:183], v[84:87]
	v_mfma_f32_16x16x32_bf16 v[80:83], v[144:147], v[188:191], v[80:83]
	v_mfma_f32_16x16x32_bf16 v[76:79], v[152:155], v[188:191], v[76:79]
	v_mfma_f32_16x16x32_bf16 v[64:67], v[144:147], v[196:199], v[64:67]
	v_mfma_f32_16x16x32_bf16 v[60:63], v[152:155], v[196:199], v[60:63]
	s_barrier
	s_add_u32 s4, s4, 0x40080
	s_addc_u32 s5, s5, 0
	s_add_i32 s16, s16, s23
	v_lshl_add_u64 v[140:141], s[4:5], 0, v[2:3]
	s_mov_b32 m0, s16
	s_nop 0
	global_load_lds_dwordx4 v[140:141], off
	v_lshl_add_u64 v[140:141], s[4:5], 0, v[0:1]
	s_add_i32 m0, s16, 0x2000
	s_nop 0
	global_load_lds_dwordx4 v[140:141], off
	s_waitcnt vmcnt(6)
	s_barrier
	v_mfma_f32_16x16x32_bf16 v[32:35], v[200:203], v[160:163], v[32:35]
	v_mfma_f32_16x16x32_bf16 v[28:31], v[208:211], v[160:163], v[28:31]
	v_mfma_f32_16x16x32_bf16 v[24:27], v[200:203], v[176:179], v[24:27]
	v_mfma_f32_16x16x32_bf16 v[20:23], v[208:211], v[176:179], v[20:23]
	v_mfma_f32_16x16x32_bf16 v[16:19], v[200:203], v[184:187], v[16:19]
	v_mfma_f32_16x16x32_bf16 v[12:15], v[208:211], v[184:187], v[12:15]
	v_mfma_f32_16x16x32_bf16 v[8:11], v[200:203], v[192:195], v[8:11]
	v_mfma_f32_16x16x32_bf16 v[4:7], v[208:211], v[192:195], v[4:7]
	v_mfma_f32_16x16x32_bf16 v[32:35], v[204:207], v[172:175], v[32:35]
	v_mfma_f32_16x16x32_bf16 v[28:31], v[220:223], v[172:175], v[28:31]
	v_mfma_f32_16x16x32_bf16 v[24:27], v[204:207], v[180:183], v[24:27]
	v_mfma_f32_16x16x32_bf16 v[20:23], v[220:223], v[180:183], v[20:23]
	v_mfma_f32_16x16x32_bf16 v[16:19], v[204:207], v[188:191], v[16:19]
	v_mfma_f32_16x16x32_bf16 v[12:15], v[220:223], v[188:191], v[12:15]
	v_mfma_f32_16x16x32_bf16 v[8:11], v[204:207], v[196:199], v[8:11]
	v_mfma_f32_16x16x32_bf16 v[4:7], v[220:223], v[196:199], v[4:7]
	s_add_i32 s53, s53, 2
	s_add_u32 s2, s2, 0x100
	s_addc_u32 s3, s3, 0
	s_add_u32 s9, s9, 0x100
	s_addc_u32 s11, s11, 0
	s_cmp_gt_u32 s53, 13
	s_barrier
	s_cbranch_scc0 .LBB0_1098
	v_lshl_add_u32 v154, s37, 8, v156
	v_ashrrev_i32_e32 v155, 31, v154
	v_lshl_add_u64 v[168:169], v[154:155], 2, s[70:71]
	global_load_dword v174, v[168:169], off
	global_load_dword v173, v[168:169], off offset:64
	global_load_dword v172, v[168:169], off offset:128
	global_load_dword v170, v[168:169], off offset:192
	global_load_dword v163, v[168:169], off offset:512
	global_load_dword v162, v[168:169], off offset:576
	global_load_dword v161, v[168:169], off offset:640
	global_load_dword v160, v[168:169], off offset:704
	v_lshl_or_b32 v168, s36, 8, v158
	v_ashrrev_i32_e32 v169, 31, v168
	v_or_b32_e32 v152, 16, v154
	v_ashrrev_i32_e32 v153, 31, v152
	v_or_b32_e32 v150, 32, v154
	v_ashrrev_i32_e32 v151, 31, v150
	v_or_b32_e32 v148, 48, v154
	v_ashrrev_i32_e32 v149, 31, v148
	v_add_u32_e32 v146, 0x80, v154
	v_ashrrev_i32_e32 v147, 31, v146
	v_add_u32_e32 v144, 0x90, v154
	v_ashrrev_i32_e32 v145, 31, v144
	v_add_u32_e32 v142, 0xa0, v154
	v_ashrrev_i32_e32 v143, 31, v142
	v_add_u32_e32 v140, 0xb0, v154
	v_ashrrev_i32_e32 v141, 31, v140
	v_readlane_b32 s72, v255, 28
	s_and_b64 vcc, exec, s[46:47]
	s_mov_b32 s36, s8
	s_mov_b32 s37, s10
	s_mov_b64 s[4:5], s[20:21]
	s_mov_b64 s[2:3], s[48:49]
	v_readlane_b32 s73, v255, 29
	s_waitcnt vmcnt(0)
	v_mul_f32_e32 v124, v124, v174
	v_mul_f32_e32 v125, v125, v174
	v_max_f32_e32 v124, 0, v124
	v_max_f32_e32 v125, 0, v125
	v_pk_mul_f32 v[176:177], v[124:125], v[124:125]
	v_mul_f32_e32 v125, v126, v174
	v_mul_f32_e32 v124, v174, v130
	v_max_f32_e32 v126, 0, v125
	v_mul_f32_e32 v125, v174, v131
	v_mul_f32_e32 v128, v174, v128
	v_mul_f32_e32 v129, v174, v129
	v_max_f32_e32 v124, 0, v124
	v_max_f32_e32 v125, 0, v125
	v_mul_f32_e32 v127, v127, v174
	v_max_f32_e32 v128, 0, v128
	v_max_f32_e32 v129, 0, v129
	v_max_f32_e32 v127, 0, v127
	v_pk_mul_f32 v[130:131], v[124:125], v[124:125]
	v_lshlrev_b64 v[124:125], 13, v[154:155]
	v_pk_mul_f32 v[128:129], v[128:129], v[128:129]
	v_pk_mul_f32 v[178:179], v[126:127], v[126:127]
	v_lshl_add_u64 v[124:125], s[94:95], 0, v[124:125]
	v_lshlrev_b64 v[126:127], 1, v[168:169]
	v_mul_f32_e32 v116, v116, v173
	v_mul_f32_e32 v117, v117, v173
	v_lshl_add_u64 v[124:125], v[124:125], 0, v[126:127]
	v_cvt_pk_bf16_f32 v128, v128, v129
	v_cvt_pk_bf16_f32 v129, v130, v131
	v_cvt_pk_bf16_f32 v130, v176, v177
	v_cvt_pk_bf16_f32 v131, v178, v179
	v_max_f32_e32 v116, 0, v116
	v_max_f32_e32 v117, 0, v117
	global_store_dwordx4 v[124:125], v[128:131], off
	v_mul_f32_e32 v120, v120, v173
	v_mul_f32_e32 v121, v121, v173
	v_pk_mul_f32 v[128:129], v[116:117], v[116:117]
	v_mul_f32_e32 v117, v118, v173
	v_mul_f32_e32 v116, v122, v173
	v_max_f32_e32 v118, 0, v117
	v_mul_f32_e32 v117, v123, v173
	v_max_f32_e32 v116, 0, v116
	v_max_f32_e32 v117, 0, v117
	v_mul_f32_e32 v119, v119, v173
	v_max_f32_e32 v120, 0, v120
	v_max_f32_e32 v121, 0, v121
	v_max_f32_e32 v119, 0, v119
	v_pk_mul_f32 v[122:123], v[116:117], v[116:117]
	v_lshlrev_b64 v[116:117], 13, v[152:153]
	v_pk_mul_f32 v[120:121], v[120:121], v[120:121]
	v_pk_mul_f32 v[130:131], v[118:119], v[118:119]
	v_lshl_add_u64 v[116:117], s[94:95], 0, v[116:117]
	v_mul_f32_e32 v108, v108, v172
	v_mul_f32_e32 v109, v109, v172
	v_lshl_add_u64 v[116:117], v[116:117], 0, v[126:127]
	v_cvt_pk_bf16_f32 v118, v120, v121
	v_cvt_pk_bf16_f32 v119, v122, v123
	v_cvt_pk_bf16_f32 v120, v128, v129
	v_cvt_pk_bf16_f32 v121, v130, v131
	v_max_f32_e32 v108, 0, v108
	v_max_f32_e32 v109, 0, v109
	global_store_dwordx4 v[116:117], v[118:121], off
	v_mul_f32_e32 v112, v112, v172
	v_mul_f32_e32 v113, v113, v172
	v_pk_mul_f32 v[118:119], v[108:109], v[108:109]
	v_mul_f32_e32 v109, v110, v172
	v_mul_f32_e32 v108, v114, v172
	v_max_f32_e32 v110, 0, v109
	v_mul_f32_e32 v109, v115, v172
	v_max_f32_e32 v108, 0, v108
	v_max_f32_e32 v109, 0, v109
	v_mul_f32_e32 v111, v111, v172
	v_max_f32_e32 v112, 0, v112
	v_max_f32_e32 v113, 0, v113
	v_max_f32_e32 v111, 0, v111
	v_pk_mul_f32 v[114:115], v[108:109], v[108:109]
	v_lshlrev_b64 v[108:109], 13, v[150:151]
	v_pk_mul_f32 v[112:113], v[112:113], v[112:113]
	v_pk_mul_f32 v[120:121], v[110:111], v[110:111]
	v_lshl_add_u64 v[108:109], s[94:95], 0, v[108:109]
	v_mul_f32_e32 v100, v100, v170
	v_mul_f32_e32 v101, v101, v170
	v_lshl_add_u64 v[108:109], v[108:109], 0, v[126:127]
	v_cvt_pk_bf16_f32 v110, v112, v113
	v_cvt_pk_bf16_f32 v111, v114, v115
	v_cvt_pk_bf16_f32 v112, v118, v119
	v_cvt_pk_bf16_f32 v113, v120, v121
	v_max_f32_e32 v100, 0, v100
	v_max_f32_e32 v101, 0, v101
	global_store_dwordx4 v[108:109], v[110:113], off
	v_mul_f32_e32 v104, v104, v170
	v_mul_f32_e32 v105, v105, v170
	v_pk_mul_f32 v[110:111], v[100:101], v[100:101]
	v_mul_f32_e32 v101, v102, v170
	v_mul_f32_e32 v100, v106, v170
	v_max_f32_e32 v102, 0, v101
	v_mul_f32_e32 v101, v107, v170
	v_max_f32_e32 v100, 0, v100
	v_max_f32_e32 v101, 0, v101
	v_mul_f32_e32 v103, v103, v170
	v_max_f32_e32 v104, 0, v104
	v_max_f32_e32 v105, 0, v105
	v_max_f32_e32 v103, 0, v103
	v_pk_mul_f32 v[106:107], v[100:101], v[100:101]
	v_lshlrev_b64 v[100:101], 13, v[148:149]
	v_pk_mul_f32 v[104:105], v[104:105], v[104:105]
	v_pk_mul_f32 v[112:113], v[102:103], v[102:103]
	v_lshl_add_u64 v[100:101], s[94:95], 0, v[100:101]
	v_mul_f32_e32 v92, v92, v163
	v_mul_f32_e32 v93, v93, v163
	v_lshl_add_u64 v[100:101], v[100:101], 0, v[126:127]
	v_cvt_pk_bf16_f32 v102, v104, v105
	v_cvt_pk_bf16_f32 v103, v106, v107
	v_cvt_pk_bf16_f32 v104, v110, v111
	v_cvt_pk_bf16_f32 v105, v112, v113
	v_max_f32_e32 v92, 0, v92
	v_max_f32_e32 v93, 0, v93
	global_store_dwordx4 v[100:101], v[102:105], off
	v_mul_f32_e32 v96, v96, v163
	v_mul_f32_e32 v97, v97, v163
	v_pk_mul_f32 v[102:103], v[92:93], v[92:93]
	v_mul_f32_e32 v93, v94, v163
	v_mul_f32_e32 v92, v98, v163
	v_max_f32_e32 v94, 0, v93
	v_mul_f32_e32 v93, v99, v163
	v_max_f32_e32 v92, 0, v92
	v_max_f32_e32 v93, 0, v93
	v_mul_f32_e32 v95, v95, v163
	v_max_f32_e32 v96, 0, v96
	v_max_f32_e32 v97, 0, v97
	v_max_f32_e32 v95, 0, v95
	v_pk_mul_f32 v[98:99], v[92:93], v[92:93]
	v_lshlrev_b64 v[92:93], 13, v[146:147]
	v_pk_mul_f32 v[96:97], v[96:97], v[96:97]
	v_pk_mul_f32 v[104:105], v[94:95], v[94:95]
	v_lshl_add_u64 v[92:93], s[94:95], 0, v[92:93]
	v_mul_f32_e32 v84, v84, v162
	v_mul_f32_e32 v85, v85, v162
	v_lshl_add_u64 v[92:93], v[92:93], 0, v[126:127]
	v_cvt_pk_bf16_f32 v94, v96, v97
	v_cvt_pk_bf16_f32 v95, v98, v99
	v_cvt_pk_bf16_f32 v96, v102, v103
	v_cvt_pk_bf16_f32 v97, v104, v105
	v_max_f32_e32 v84, 0, v84
	v_max_f32_e32 v85, 0, v85
	global_store_dwordx4 v[92:93], v[94:97], off
	v_mul_f32_e32 v88, v88, v162
	v_mul_f32_e32 v89, v89, v162
	v_pk_mul_f32 v[94:95], v[84:85], v[84:85]
	v_mul_f32_e32 v85, v86, v162
	v_mul_f32_e32 v84, v90, v162
	v_max_f32_e32 v86, 0, v85
	v_mul_f32_e32 v85, v91, v162
	v_max_f32_e32 v84, 0, v84
	v_max_f32_e32 v85, 0, v85
	v_mul_f32_e32 v87, v87, v162
	v_max_f32_e32 v88, 0, v88
	v_max_f32_e32 v89, 0, v89
	v_max_f32_e32 v87, 0, v87
	v_pk_mul_f32 v[90:91], v[84:85], v[84:85]
	v_lshlrev_b64 v[84:85], 13, v[144:145]
	v_pk_mul_f32 v[88:89], v[88:89], v[88:89]
	v_pk_mul_f32 v[96:97], v[86:87], v[86:87]
	v_lshl_add_u64 v[84:85], s[94:95], 0, v[84:85]
	v_mul_f32_e32 v76, v76, v161
	v_mul_f32_e32 v77, v77, v161
	v_lshl_add_u64 v[84:85], v[84:85], 0, v[126:127]
	v_cvt_pk_bf16_f32 v86, v88, v89
	v_cvt_pk_bf16_f32 v87, v90, v91
	v_cvt_pk_bf16_f32 v88, v94, v95
	v_cvt_pk_bf16_f32 v89, v96, v97
	v_max_f32_e32 v76, 0, v76
	v_max_f32_e32 v77, 0, v77
	global_store_dwordx4 v[84:85], v[86:89], off
	v_mul_f32_e32 v80, v80, v161
	v_mul_f32_e32 v81, v81, v161
	v_pk_mul_f32 v[86:87], v[76:77], v[76:77]
	v_mul_f32_e32 v77, v78, v161
	v_mul_f32_e32 v76, v82, v161
	v_max_f32_e32 v78, 0, v77
	v_mul_f32_e32 v77, v83, v161
	v_max_f32_e32 v76, 0, v76
	v_max_f32_e32 v77, 0, v77
	v_mul_f32_e32 v79, v79, v161
	v_max_f32_e32 v80, 0, v80
	v_max_f32_e32 v81, 0, v81
	v_max_f32_e32 v79, 0, v79
	v_pk_mul_f32 v[82:83], v[76:77], v[76:77]
	v_lshlrev_b64 v[76:77], 13, v[142:143]
	v_pk_mul_f32 v[80:81], v[80:81], v[80:81]
	v_pk_mul_f32 v[88:89], v[78:79], v[78:79]
	v_lshl_add_u64 v[76:77], s[94:95], 0, v[76:77]
	v_mul_f32_e32 v60, v60, v160
	v_mul_f32_e32 v61, v61, v160
	v_lshl_add_u64 v[76:77], v[76:77], 0, v[126:127]
	v_cvt_pk_bf16_f32 v78, v80, v81
	v_cvt_pk_bf16_f32 v79, v82, v83
	v_cvt_pk_bf16_f32 v80, v86, v87
	v_cvt_pk_bf16_f32 v81, v88, v89
	v_max_f32_e32 v60, 0, v60
	v_max_f32_e32 v61, 0, v61
	global_store_dwordx4 v[76:77], v[78:81], off
	v_mul_f32_e32 v64, v64, v160
	v_mul_f32_e32 v65, v65, v160
	v_pk_mul_f32 v[78:79], v[60:61], v[60:61]
	v_mul_f32_e32 v61, v62, v160
	v_mul_f32_e32 v60, v66, v160
	v_max_f32_e32 v62, 0, v61
	v_mul_f32_e32 v61, v67, v160
	v_max_f32_e32 v60, 0, v60
	v_max_f32_e32 v61, 0, v61
	v_mul_f32_e32 v63, v63, v160
	v_max_f32_e32 v64, 0, v64
	v_max_f32_e32 v65, 0, v65
	v_max_f32_e32 v63, 0, v63
	v_pk_mul_f32 v[66:67], v[60:61], v[60:61]
	v_lshlrev_b64 v[60:61], 13, v[140:141]
	v_pk_mul_f32 v[64:65], v[64:65], v[64:65]
	v_pk_mul_f32 v[80:81], v[62:63], v[62:63]
	v_lshl_add_u64 v[60:61], s[94:95], 0, v[60:61]
	v_lshl_add_u64 v[60:61], v[60:61], 0, v[126:127]
	v_cvt_pk_bf16_f32 v62, v64, v65
	v_cvt_pk_bf16_f32 v63, v66, v67
	v_cvt_pk_bf16_f32 v64, v78, v79
	v_cvt_pk_bf16_f32 v65, v80, v81
	global_store_dwordx4 v[60:61], v[62:65], off
	v_mul_f32_e32 v67, v70, v174
	v_mul_f32_e32 v66, v74, v174
	v_mul_f32_e32 v63, v68, v174
	v_mul_f32_e32 v62, v72, v174
	v_max_f32_e32 v64, 0, v63
	v_mul_f32_e32 v63, v73, v174
	v_mul_f32_e32 v65, v69, v174
	v_max_f32_e32 v68, 0, v67
	v_mul_f32_e32 v67, v75, v174
	v_mul_f32_e32 v69, v71, v174
	v_max_f32_e32 v62, 0, v62
	v_max_f32_e32 v63, 0, v63
	v_max_f32_e32 v65, 0, v65
	v_max_f32_e32 v66, 0, v66
	v_max_f32_e32 v67, 0, v67
	v_max_f32_e32 v69, 0, v69
	v_pk_mul_f32 v[62:63], v[62:63], v[62:63]
	v_pk_mul_f32 v[64:65], v[64:65], v[64:65]
	v_pk_mul_f32 v[66:67], v[66:67], v[66:67]
	v_pk_mul_f32 v[68:69], v[68:69], v[68:69]
	v_mul_f32_e32 v52, v52, v173
	v_mul_f32_e32 v53, v53, v173
	v_cvt_pk_bf16_f32 v62, v62, v63
	v_cvt_pk_bf16_f32 v63, v66, v67
	v_cvt_pk_bf16_f32 v64, v64, v65
	v_cvt_pk_bf16_f32 v65, v68, v69
	v_max_f32_e32 v52, 0, v52
	v_max_f32_e32 v53, 0, v53
	global_store_dwordx4 v[124:125], v[62:65], off offset:256
	v_mul_f32_e32 v56, v56, v173
	v_mul_f32_e32 v57, v57, v173
	v_pk_mul_f32 v[62:63], v[52:53], v[52:53]
	v_mul_f32_e32 v53, v54, v173
	v_mul_f32_e32 v52, v58, v173
	v_max_f32_e32 v54, 0, v53
	v_mul_f32_e32 v53, v59, v173
	v_mul_f32_e32 v55, v55, v173
	v_max_f32_e32 v56, 0, v56
	v_max_f32_e32 v57, 0, v57
	v_max_f32_e32 v52, 0, v52
	v_max_f32_e32 v53, 0, v53
	v_max_f32_e32 v55, 0, v55
	v_pk_mul_f32 v[56:57], v[56:57], v[56:57]
	v_pk_mul_f32 v[58:59], v[52:53], v[52:53]
	v_pk_mul_f32 v[64:65], v[54:55], v[54:55]
	v_mul_f32_e32 v44, v44, v172
	v_mul_f32_e32 v45, v45, v172
	v_cvt_pk_bf16_f32 v52, v56, v57
	v_cvt_pk_bf16_f32 v53, v58, v59
	v_cvt_pk_bf16_f32 v54, v62, v63
	v_cvt_pk_bf16_f32 v55, v64, v65
	v_max_f32_e32 v44, 0, v44
	v_max_f32_e32 v45, 0, v45
	global_store_dwordx4 v[116:117], v[52:55], off offset:256
	v_mul_f32_e32 v48, v48, v172
	v_mul_f32_e32 v49, v49, v172
	v_pk_mul_f32 v[52:53], v[44:45], v[44:45]
	v_mul_f32_e32 v45, v46, v172
	v_mul_f32_e32 v44, v50, v172
	v_max_f32_e32 v46, 0, v45
	v_mul_f32_e32 v45, v51, v172
	v_mul_f32_e32 v47, v47, v172
	v_max_f32_e32 v48, 0, v48
	v_max_f32_e32 v49, 0, v49
	v_max_f32_e32 v44, 0, v44
	v_max_f32_e32 v45, 0, v45
	v_max_f32_e32 v47, 0, v47
	v_pk_mul_f32 v[48:49], v[48:49], v[48:49]
	v_pk_mul_f32 v[50:51], v[44:45], v[44:45]
	v_pk_mul_f32 v[54:55], v[46:47], v[46:47]
	v_mul_f32_e32 v36, v36, v170
	v_mul_f32_e32 v37, v37, v170
	v_cvt_pk_bf16_f32 v44, v48, v49
	v_cvt_pk_bf16_f32 v45, v50, v51
	v_cvt_pk_bf16_f32 v46, v52, v53
	v_cvt_pk_bf16_f32 v47, v54, v55
	v_max_f32_e32 v36, 0, v36
	v_max_f32_e32 v37, 0, v37
	global_store_dwordx4 v[108:109], v[44:47], off offset:256
	v_mul_f32_e32 v40, v40, v170
	v_mul_f32_e32 v41, v41, v170
	v_pk_mul_f32 v[44:45], v[36:37], v[36:37]
	v_mul_f32_e32 v37, v38, v170
	v_mul_f32_e32 v36, v42, v170
	v_max_f32_e32 v38, 0, v37
	v_mul_f32_e32 v37, v43, v170
	v_mul_f32_e32 v39, v39, v170
	v_max_f32_e32 v40, 0, v40
	v_max_f32_e32 v41, 0, v41
	v_max_f32_e32 v36, 0, v36
	v_max_f32_e32 v37, 0, v37
	v_max_f32_e32 v39, 0, v39
	v_pk_mul_f32 v[40:41], v[40:41], v[40:41]
	v_pk_mul_f32 v[42:43], v[36:37], v[36:37]
	v_pk_mul_f32 v[46:47], v[38:39], v[38:39]
	v_mul_f32_e32 v28, v28, v163
	v_mul_f32_e32 v29, v29, v163
	v_cvt_pk_bf16_f32 v36, v40, v41
	v_cvt_pk_bf16_f32 v37, v42, v43
	v_cvt_pk_bf16_f32 v38, v44, v45
	v_cvt_pk_bf16_f32 v39, v46, v47
	v_max_f32_e32 v28, 0, v28
	v_max_f32_e32 v29, 0, v29
	global_store_dwordx4 v[100:101], v[36:39], off offset:256
	v_mul_f32_e32 v32, v32, v163
	v_mul_f32_e32 v33, v33, v163
	v_pk_mul_f32 v[36:37], v[28:29], v[28:29]
	v_mul_f32_e32 v29, v30, v163
	v_mul_f32_e32 v28, v34, v163
	v_max_f32_e32 v30, 0, v29
	v_mul_f32_e32 v29, v35, v163
	v_mul_f32_e32 v31, v31, v163
	v_max_f32_e32 v32, 0, v32
	v_max_f32_e32 v33, 0, v33
	v_max_f32_e32 v28, 0, v28
	v_max_f32_e32 v29, 0, v29
	v_max_f32_e32 v31, 0, v31
	v_pk_mul_f32 v[32:33], v[32:33], v[32:33]
	v_pk_mul_f32 v[34:35], v[28:29], v[28:29]
	v_pk_mul_f32 v[38:39], v[30:31], v[30:31]
	v_mul_f32_e32 v20, v20, v162
	v_mul_f32_e32 v21, v21, v162
	v_cvt_pk_bf16_f32 v28, v32, v33
	v_cvt_pk_bf16_f32 v29, v34, v35
	v_cvt_pk_bf16_f32 v30, v36, v37
	v_cvt_pk_bf16_f32 v31, v38, v39
	v_max_f32_e32 v20, 0, v20
	v_max_f32_e32 v21, 0, v21
	global_store_dwordx4 v[92:93], v[28:31], off offset:256
	v_mul_f32_e32 v24, v24, v162
	v_mul_f32_e32 v25, v25, v162
	v_pk_mul_f32 v[28:29], v[20:21], v[20:21]
	v_mul_f32_e32 v21, v22, v162
	v_mul_f32_e32 v20, v26, v162
	v_max_f32_e32 v22, 0, v21
	v_mul_f32_e32 v21, v27, v162
	v_mul_f32_e32 v23, v23, v162
	v_max_f32_e32 v24, 0, v24
	v_max_f32_e32 v25, 0, v25
	v_max_f32_e32 v20, 0, v20
	v_max_f32_e32 v21, 0, v21
	v_max_f32_e32 v23, 0, v23
	v_pk_mul_f32 v[24:25], v[24:25], v[24:25]
	v_pk_mul_f32 v[26:27], v[20:21], v[20:21]
	v_pk_mul_f32 v[30:31], v[22:23], v[22:23]
	v_mul_f32_e32 v12, v12, v161
	v_mul_f32_e32 v13, v13, v161
	v_cvt_pk_bf16_f32 v20, v24, v25
	v_cvt_pk_bf16_f32 v21, v26, v27
	v_cvt_pk_bf16_f32 v22, v28, v29
	v_cvt_pk_bf16_f32 v23, v30, v31
	v_max_f32_e32 v12, 0, v12
	v_max_f32_e32 v13, 0, v13
	global_store_dwordx4 v[84:85], v[20:23], off offset:256
	v_mul_f32_e32 v16, v16, v161
	v_mul_f32_e32 v17, v17, v161
	v_pk_mul_f32 v[20:21], v[12:13], v[12:13]
	v_mul_f32_e32 v13, v14, v161
	v_mul_f32_e32 v12, v18, v161
	v_max_f32_e32 v14, 0, v13
	v_mul_f32_e32 v13, v19, v161
	v_mul_f32_e32 v15, v15, v161
	v_max_f32_e32 v16, 0, v16
	v_max_f32_e32 v17, 0, v17
	v_max_f32_e32 v12, 0, v12
	v_max_f32_e32 v13, 0, v13
	v_max_f32_e32 v15, 0, v15
	v_pk_mul_f32 v[16:17], v[16:17], v[16:17]
	v_pk_mul_f32 v[18:19], v[12:13], v[12:13]
	v_pk_mul_f32 v[22:23], v[14:15], v[14:15]
	v_mul_f32_e32 v4, v4, v160
	v_mul_f32_e32 v5, v5, v160
	v_cvt_pk_bf16_f32 v12, v16, v17
	v_cvt_pk_bf16_f32 v13, v18, v19
	v_cvt_pk_bf16_f32 v14, v20, v21
	v_cvt_pk_bf16_f32 v15, v22, v23
	v_max_f32_e32 v4, 0, v4
	v_max_f32_e32 v5, 0, v5
	global_store_dwordx4 v[76:77], v[12:15], off offset:256
	v_mul_f32_e32 v8, v8, v160
	v_mul_f32_e32 v9, v9, v160
	v_pk_mul_f32 v[12:13], v[4:5], v[4:5]
	v_mul_f32_e32 v5, v6, v160
	v_mul_f32_e32 v4, v10, v160
	v_max_f32_e32 v6, 0, v5
	v_mul_f32_e32 v5, v11, v160
	v_mul_f32_e32 v7, v7, v160
	v_max_f32_e32 v8, 0, v8
	v_max_f32_e32 v9, 0, v9
	v_max_f32_e32 v4, 0, v4
	v_max_f32_e32 v5, 0, v5
	v_max_f32_e32 v7, 0, v7
	v_pk_mul_f32 v[8:9], v[8:9], v[8:9]
	v_pk_mul_f32 v[10:11], v[4:5], v[4:5]
	v_pk_mul_f32 v[14:15], v[6:7], v[6:7]
	v_cvt_pk_bf16_f32 v4, v8, v9
	v_cvt_pk_bf16_f32 v5, v10, v11
	v_cvt_pk_bf16_f32 v6, v12, v13
	v_cvt_pk_bf16_f32 v7, v14, v15
	global_store_dwordx4 v[60:61], v[4:7], off offset:256
	s_cbranch_vccz .LBB0_1089
	s_waitcnt vmcnt(0)
	s_cmpk_gt_u32 s22, 0xff
	v_readlane_b32 s36, v254, 31
	v_readlane_b32 s37, v254, 32
	s_cbranch_scc1 .LBB0_1102
	s_barrier

.LBB0_1175:
	s_add_u32 s16, s20, 0xfff00080
	s_addc_u32 s17, s21, -1
	s_add_i32 s49, 0, 0x10000
	v_add_u32_e32 v147, s49, v141
	ds_read_b128 v[148:151], v147
	ds_read_b128 v[152:155], v147 offset:1024
	ds_read_b128 v[156:159], v147 offset:2048
	ds_read_b128 v[160:163], v147 offset:3072
	s_cmp_eq_u32 s48, 60
	s_cselect_b32 s17, s9, s17
	s_cselect_b32 s16, s8, s16
	s_cselect_b32 s23, s11, s5
	s_cselect_b32 s22, s10, s3
	v_lshl_add_u64 v[168:169], s[20:21], 0, v[136:137]
	s_add_i32 m0, s30, 0xc000
	ds_read_b128 v[172:175], v146
	ds_read_b128 v[176:179], v146 offset:1024
	ds_read_b128 v[180:183], v146 offset:2048
	ds_read_b128 v[184:187], v146 offset:3072
	ds_read_b128 v[188:191], v146 offset:4096
	ds_read_b128 v[192:195], v146 offset:5120
	ds_read_b128 v[196:199], v146 offset:6144
	ds_read_b128 v[200:203], v146 offset:7168
	global_load_lds_dwordx4 v[168:169], off
	v_lshl_add_u64 v[168:169], s[20:21], 0, v[138:139]
	s_add_i32 m0, s30, 0xe000
	s_nop 0
	global_load_lds_dwordx4 v[168:169], off
	s_waitcnt lgkmcnt(8)
	s_barrier
	s_waitcnt lgkmcnt(0)
	s_waitcnt lgkmcnt(0)
	v_mfma_f32_16x16x32_bf16 v[128:131], v[148:151], v[172:175], v[128:131]
	v_mfma_f32_16x16x32_bf16 v[124:127], v[156:159], v[172:175], v[124:127]
	v_mfma_f32_16x16x32_bf16 v[120:123], v[148:151], v[180:183], v[120:123]
	v_mfma_f32_16x16x32_bf16 v[116:119], v[156:159], v[180:183], v[116:119]
	v_mfma_f32_16x16x32_bf16 v[112:115], v[148:151], v[188:191], v[112:115]
	v_mfma_f32_16x16x32_bf16 v[108:111], v[156:159], v[188:191], v[108:111]
	v_mfma_f32_16x16x32_bf16 v[104:107], v[148:151], v[196:199], v[104:107]
	v_mfma_f32_16x16x32_bf16 v[100:103], v[156:159], v[196:199], v[100:103]
	v_mfma_f32_16x16x32_bf16 v[128:131], v[152:155], v[176:179], v[128:131]
	v_mfma_f32_16x16x32_bf16 v[124:127], v[160:163], v[176:179], v[124:127]
	v_mfma_f32_16x16x32_bf16 v[120:123], v[152:155], v[184:187], v[120:123]
	v_mfma_f32_16x16x32_bf16 v[116:119], v[160:163], v[184:187], v[116:119]
	v_mfma_f32_16x16x32_bf16 v[112:115], v[152:155], v[192:195], v[112:115]
	v_mfma_f32_16x16x32_bf16 v[108:111], v[160:163], v[192:195], v[108:111]
	v_mfma_f32_16x16x32_bf16 v[104:107], v[152:155], v[200:203], v[104:107]
	v_mfma_f32_16x16x32_bf16 v[100:103], v[160:163], v[200:203], v[100:103]
	s_barrier
	s_add_i32 s73, 0, 0x14000
	s_add_i32 s49, s49, s27
	v_add_u32_e32 v147, s73, v141
	v_lshl_add_u64 v[168:169], s[22:23], 0, v[2:3]
	s_mov_b32 m0, s49
	ds_read_b128 v[204:207], v147
	ds_read_b128 v[208:211], v147 offset:1024
	ds_read_b128 v[220:223], v147 offset:2048
	ds_read_b128 v[234:237], v147 offset:3072
	global_load_lds_dwordx4 v[168:169], off
	v_lshl_add_u64 v[214:215], s[22:23], 0, v[0:1]
	s_add_i32 m0, s49, 0x2000
	s_nop 0
	global_load_lds_dwordx4 v[214:215], off
	s_barrier
	s_waitcnt lgkmcnt(0)
	s_waitcnt lgkmcnt(0)
	v_mfma_f32_16x16x32_bf16 v[84:87], v[204:207], v[172:175], v[84:87]
	v_mfma_f32_16x16x32_bf16 v[76:79], v[220:223], v[172:175], v[76:79]
	v_mfma_f32_16x16x32_bf16 v[72:75], v[204:207], v[180:183], v[72:75]
	v_mfma_f32_16x16x32_bf16 v[68:71], v[220:223], v[180:183], v[68:71]
	v_mfma_f32_16x16x32_bf16 v[56:59], v[204:207], v[188:191], v[56:59]
	v_mfma_f32_16x16x32_bf16 v[52:55], v[220:223], v[188:191], v[52:55]
	v_mfma_f32_16x16x32_bf16 v[44:47], v[204:207], v[196:199], v[44:47]
	v_mfma_f32_16x16x32_bf16 v[36:39], v[220:223], v[196:199], v[36:39]
	v_mfma_f32_16x16x32_bf16 v[84:87], v[208:211], v[176:179], v[84:87]
	v_mfma_f32_16x16x32_bf16 v[76:79], v[234:237], v[176:179], v[76:79]
	v_mfma_f32_16x16x32_bf16 v[72:75], v[208:211], v[184:187], v[72:75]
	v_mfma_f32_16x16x32_bf16 v[68:71], v[234:237], v[184:187], v[68:71]
	v_mfma_f32_16x16x32_bf16 v[56:59], v[208:211], v[192:195], v[56:59]
	v_mfma_f32_16x16x32_bf16 v[52:55], v[234:237], v[192:195], v[52:55]
	v_mfma_f32_16x16x32_bf16 v[44:47], v[208:211], v[200:203], v[44:47]
	v_mfma_f32_16x16x32_bf16 v[36:39], v[234:237], v[200:203], v[36:39]
	s_mov_b32 m0, s30
	v_lshl_add_u64 v[224:225], s[16:17], 0, v[134:135]
	s_barrier
	ds_read_b128 v[172:175], v146 offset:16384
	ds_read_b128 v[176:179], v146 offset:17408
	ds_read_b128 v[180:183], v146 offset:18432
	ds_read_b128 v[184:187], v146 offset:19456
	ds_read_b128 v[188:191], v146 offset:20480
	ds_read_b128 v[192:195], v146 offset:21504
	ds_read_b128 v[196:199], v146 offset:22528
	ds_read_b128 v[200:203], v146 offset:23552
	global_load_lds_dwordx4 v[224:225], off
	v_lshl_add_u64 v[238:239], s[16:17], 0, v[132:133]
	s_mov_b32 m0, s31
	s_nop 0
	global_load_lds_dwordx4 v[238:239], off
	s_barrier
	s_waitcnt lgkmcnt(0)
	s_waitcnt lgkmcnt(0)
	v_mfma_f32_16x16x32_bf16 v[96:99], v[148:151], v[172:175], v[96:99]
	v_mfma_f32_16x16x32_bf16 v[92:95], v[156:159], v[172:175], v[92:95]
	v_mfma_f32_16x16x32_bf16 v[88:91], v[148:151], v[180:183], v[88:91]
	v_mfma_f32_16x16x32_bf16 v[80:83], v[156:159], v[180:183], v[80:83]
	v_mfma_f32_16x16x32_bf16 v[64:67], v[148:151], v[188:191], v[64:67]
	v_mfma_f32_16x16x32_bf16 v[60:63], v[156:159], v[188:191], v[60:63]
	v_mfma_f32_16x16x32_bf16 v[48:51], v[148:151], v[196:199], v[48:51]
	v_mfma_f32_16x16x32_bf16 v[40:43], v[156:159], v[196:199], v[40:43]
	v_mfma_f32_16x16x32_bf16 v[96:99], v[152:155], v[176:179], v[96:99]
	v_mfma_f32_16x16x32_bf16 v[92:95], v[160:163], v[176:179], v[92:95]
	v_mfma_f32_16x16x32_bf16 v[88:91], v[152:155], v[184:187], v[88:91]
	v_mfma_f32_16x16x32_bf16 v[80:83], v[160:163], v[184:187], v[80:83]
	v_mfma_f32_16x16x32_bf16 v[64:67], v[152:155], v[192:195], v[64:67]
	v_mfma_f32_16x16x32_bf16 v[60:63], v[160:163], v[192:195], v[60:63]
	v_mfma_f32_16x16x32_bf16 v[48:51], v[152:155], v[200:203], v[48:51]
	v_mfma_f32_16x16x32_bf16 v[40:43], v[160:163], v[200:203], v[40:43]
	s_barrier
	s_add_u32 s74, s22, 0x100000
	s_addc_u32 s75, s23, 0
	s_add_i32 s49, s73, s27
	v_lshl_add_u64 v[148:149], s[74:75], 0, v[2:3]
	s_mov_b32 m0, s49
	s_nop 0
	global_load_lds_dwordx4 v[148:149], off
	v_lshl_add_u64 v[148:149], s[74:75], 0, v[0:1]
	s_add_i32 m0, s49, 0x2000
	s_nop 0
	global_load_lds_dwordx4 v[148:149], off
	s_waitcnt vmcnt(6)
	s_barrier
	v_mfma_f32_16x16x32_bf16 v[32:35], v[204:207], v[172:175], v[32:35]
	v_mfma_f32_16x16x32_bf16 v[28:31], v[220:223], v[172:175], v[28:31]
	v_mfma_f32_16x16x32_bf16 v[24:27], v[204:207], v[180:183], v[24:27]
	v_mfma_f32_16x16x32_bf16 v[20:23], v[220:223], v[180:183], v[20:23]
	v_mfma_f32_16x16x32_bf16 v[16:19], v[204:207], v[188:191], v[16:19]
	v_mfma_f32_16x16x32_bf16 v[12:15], v[220:223], v[188:191], v[12:15]
	v_mfma_f32_16x16x32_bf16 v[8:11], v[204:207], v[196:199], v[8:11]
	v_mfma_f32_16x16x32_bf16 v[4:7], v[220:223], v[196:199], v[4:7]
	v_mfma_f32_16x16x32_bf16 v[32:35], v[208:211], v[176:179], v[32:35]
	v_mfma_f32_16x16x32_bf16 v[28:31], v[234:237], v[176:179], v[28:31]
	v_mfma_f32_16x16x32_bf16 v[24:27], v[208:211], v[184:187], v[24:27]
	v_mfma_f32_16x16x32_bf16 v[20:23], v[234:237], v[184:187], v[20:23]
	v_mfma_f32_16x16x32_bf16 v[16:19], v[208:211], v[192:195], v[16:19]
	v_mfma_f32_16x16x32_bf16 v[12:15], v[234:237], v[192:195], v[12:15]
	v_mfma_f32_16x16x32_bf16 v[8:11], v[208:211], v[200:203], v[8:11]
	v_mfma_f32_16x16x32_bf16 v[4:7], v[234:237], v[200:203], v[4:7]
	s_add_i32 s49, 0, 0x18000
	v_add_u32_e32 v147, s49, v141
	s_barrier
	ds_read_b128 v[148:151], v147
	ds_read_b128 v[152:155], v147 offset:1024
	ds_read_b128 v[156:159], v147 offset:2048
	ds_read_b128 v[160:163], v147 offset:3072
	s_add_u32 s16, s16, 0x100000
	s_addc_u32 s17, s17, 0
	s_mov_b32 m0, s36
	v_lshl_add_u64 v[204:205], s[16:17], 0, v[134:135]
	ds_read_b128 v[172:175], v146 offset:32768
	ds_read_b128 v[176:179], v146 offset:33792
	ds_read_b128 v[180:183], v146 offset:34816
	ds_read_b128 v[184:187], v146 offset:35840
	ds_read_b128 v[188:191], v146 offset:36864
	ds_read_b128 v[192:195], v146 offset:37888
	ds_read_b128 v[196:199], v146 offset:38912
	ds_read_b128 v[200:203], v146 offset:39936
	global_load_lds_dwordx4 v[204:205], off
	v_lshl_add_u64 v[204:205], s[16:17], 0, v[132:133]
	s_mov_b32 m0, s37
	s_nop 0
	global_load_lds_dwordx4 v[204:205], off
	s_waitcnt lgkmcnt(8)
	s_barrier
	s_waitcnt lgkmcnt(0)
	s_waitcnt lgkmcnt(0)
	v_mfma_f32_16x16x32_bf16 v[128:131], v[148:151], v[172:175], v[128:131]
	v_mfma_f32_16x16x32_bf16 v[124:127], v[156:159], v[172:175], v[124:127]
	v_mfma_f32_16x16x32_bf16 v[120:123], v[148:151], v[180:183], v[120:123]
	v_mfma_f32_16x16x32_bf16 v[116:119], v[156:159], v[180:183], v[116:119]
	v_mfma_f32_16x16x32_bf16 v[112:115], v[148:151], v[188:191], v[112:115]
	v_mfma_f32_16x16x32_bf16 v[108:111], v[156:159], v[188:191], v[108:111]
	v_mfma_f32_16x16x32_bf16 v[104:107], v[148:151], v[196:199], v[104:107]
	v_mfma_f32_16x16x32_bf16 v[100:103], v[156:159], v[196:199], v[100:103]
	v_mfma_f32_16x16x32_bf16 v[128:131], v[152:155], v[176:179], v[128:131]
	v_mfma_f32_16x16x32_bf16 v[124:127], v[160:163], v[176:179], v[124:127]
	v_mfma_f32_16x16x32_bf16 v[120:123], v[152:155], v[184:187], v[120:123]
	v_mfma_f32_16x16x32_bf16 v[116:119], v[160:163], v[184:187], v[116:119]
	v_mfma_f32_16x16x32_bf16 v[112:115], v[152:155], v[192:195], v[112:115]
	v_mfma_f32_16x16x32_bf16 v[108:111], v[160:163], v[192:195], v[108:111]
	v_mfma_f32_16x16x32_bf16 v[104:107], v[152:155], v[200:203], v[104:107]
	v_mfma_f32_16x16x32_bf16 v[100:103], v[160:163], v[200:203], v[100:103]
	s_barrier
	s_add_i32 s73, 0, 0x1c000
	s_add_i32 s16, s49, s27
	v_add_u32_e32 v147, s73, v141
	v_lshl_add_u64 v[168:169], v[168:169], 0, s[28:29]
	s_mov_b32 m0, s16
	ds_read_b128 v[204:207], v147
	ds_read_b128 v[208:211], v147 offset:1024
	ds_read_b128 v[220:223], v147 offset:2048
	ds_read_b128 v[234:237], v147 offset:3072
	global_load_lds_dwordx4 v[168:169], off
	v_lshl_add_u64 v[168:169], v[214:215], 0, s[28:29]
	s_add_i32 m0, s16, 0x2000
	s_nop 0
	global_load_lds_dwordx4 v[168:169], off
	s_barrier
	s_waitcnt lgkmcnt(0)
	s_waitcnt lgkmcnt(0)
	v_mfma_f32_16x16x32_bf16 v[84:87], v[204:207], v[172:175], v[84:87]
	v_mfma_f32_16x16x32_bf16 v[76:79], v[220:223], v[172:175], v[76:79]
	v_mfma_f32_16x16x32_bf16 v[72:75], v[204:207], v[180:183], v[72:75]
	v_mfma_f32_16x16x32_bf16 v[68:71], v[220:223], v[180:183], v[68:71]
	v_mfma_f32_16x16x32_bf16 v[56:59], v[204:207], v[188:191], v[56:59]
	v_mfma_f32_16x16x32_bf16 v[52:55], v[220:223], v[188:191], v[52:55]
	v_mfma_f32_16x16x32_bf16 v[44:47], v[204:207], v[196:199], v[44:47]
	v_mfma_f32_16x16x32_bf16 v[36:39], v[220:223], v[196:199], v[36:39]
	v_mfma_f32_16x16x32_bf16 v[84:87], v[208:211], v[176:179], v[84:87]
	v_mfma_f32_16x16x32_bf16 v[76:79], v[234:237], v[176:179], v[76:79]
	v_mfma_f32_16x16x32_bf16 v[72:75], v[208:211], v[184:187], v[72:75]
	v_mfma_f32_16x16x32_bf16 v[68:71], v[234:237], v[184:187], v[68:71]
	v_mfma_f32_16x16x32_bf16 v[56:59], v[208:211], v[192:195], v[56:59]
	v_mfma_f32_16x16x32_bf16 v[52:55], v[234:237], v[192:195], v[52:55]
	v_mfma_f32_16x16x32_bf16 v[44:47], v[208:211], v[200:203], v[44:47]
	v_mfma_f32_16x16x32_bf16 v[36:39], v[234:237], v[200:203], v[36:39]
	s_mov_b32 m0, s50
	v_lshl_add_u64 v[168:169], v[224:225], 0, s[28:29]
	s_barrier
	ds_read_b128 v[172:175], v146 offset:49152
	ds_read_b128 v[176:179], v146 offset:50176
	ds_read_b128 v[180:183], v146 offset:51200
	ds_read_b128 v[184:187], v146 offset:52224
	ds_read_b128 v[188:191], v146 offset:53248
	ds_read_b128 v[192:195], v146 offset:54272
	ds_read_b128 v[196:199], v146 offset:55296
	ds_read_b128 v[200:203], v146 offset:56320
	global_load_lds_dwordx4 v[168:169], off
	v_lshl_add_u64 v[168:169], v[238:239], 0, s[28:29]
	s_mov_b32 m0, s51
	s_nop 0
	global_load_lds_dwordx4 v[168:169], off
	s_barrier
	s_waitcnt lgkmcnt(0)
	s_waitcnt lgkmcnt(0)
	v_mfma_f32_16x16x32_bf16 v[96:99], v[148:151], v[172:175], v[96:99]
	v_mfma_f32_16x16x32_bf16 v[92:95], v[156:159], v[172:175], v[92:95]
	v_mfma_f32_16x16x32_bf16 v[88:91], v[148:151], v[180:183], v[88:91]
	v_mfma_f32_16x16x32_bf16 v[80:83], v[156:159], v[180:183], v[80:83]
	v_mfma_f32_16x16x32_bf16 v[64:67], v[148:151], v[188:191], v[64:67]
	v_mfma_f32_16x16x32_bf16 v[60:63], v[156:159], v[188:191], v[60:63]
	v_mfma_f32_16x16x32_bf16 v[48:51], v[148:151], v[196:199], v[48:51]
	v_mfma_f32_16x16x32_bf16 v[40:43], v[156:159], v[196:199], v[40:43]
	v_mfma_f32_16x16x32_bf16 v[96:99], v[152:155], v[176:179], v[96:99]
	v_mfma_f32_16x16x32_bf16 v[92:95], v[160:163], v[176:179], v[92:95]
	v_mfma_f32_16x16x32_bf16 v[88:91], v[152:155], v[184:187], v[88:91]
	v_mfma_f32_16x16x32_bf16 v[80:83], v[160:163], v[184:187], v[80:83]
	v_mfma_f32_16x16x32_bf16 v[64:67], v[152:155], v[192:195], v[64:67]
	v_mfma_f32_16x16x32_bf16 v[60:63], v[160:163], v[192:195], v[60:63]
	v_mfma_f32_16x16x32_bf16 v[48:51], v[152:155], v[200:203], v[48:51]
	v_mfma_f32_16x16x32_bf16 v[40:43], v[160:163], v[200:203], v[40:43]
	s_barrier
	s_add_u32 s16, s22, 0x100080
	s_addc_u32 s17, s23, 0
	s_add_i32 s22, s73, s27
	v_lshl_add_u64 v[148:149], s[16:17], 0, v[2:3]
	s_mov_b32 m0, s22
	s_nop 0
	global_load_lds_dwordx4 v[148:149], off
	v_lshl_add_u64 v[148:149], s[16:17], 0, v[0:1]
	s_add_i32 m0, s22, 0x2000
	s_nop 0
	global_load_lds_dwordx4 v[148:149], off
	s_waitcnt vmcnt(6)
	s_barrier
	v_mfma_f32_16x16x32_bf16 v[32:35], v[204:207], v[172:175], v[32:35]
	v_mfma_f32_16x16x32_bf16 v[28:31], v[220:223], v[172:175], v[28:31]
	v_mfma_f32_16x16x32_bf16 v[24:27], v[204:207], v[180:183], v[24:27]
	v_mfma_f32_16x16x32_bf16 v[20:23], v[220:223], v[180:183], v[20:23]
	v_mfma_f32_16x16x32_bf16 v[16:19], v[204:207], v[188:191], v[16:19]
	v_mfma_f32_16x16x32_bf16 v[12:15], v[220:223], v[188:191], v[12:15]
	v_mfma_f32_16x16x32_bf16 v[8:11], v[204:207], v[196:199], v[8:11]
	v_mfma_f32_16x16x32_bf16 v[4:7], v[220:223], v[196:199], v[4:7]
	v_mfma_f32_16x16x32_bf16 v[32:35], v[208:211], v[176:179], v[32:35]
	v_mfma_f32_16x16x32_bf16 v[28:31], v[234:237], v[176:179], v[28:31]
	v_mfma_f32_16x16x32_bf16 v[24:27], v[208:211], v[184:187], v[24:27]
	v_mfma_f32_16x16x32_bf16 v[20:23], v[234:237], v[184:187], v[20:23]
	v_mfma_f32_16x16x32_bf16 v[16:19], v[208:211], v[192:195], v[16:19]
	v_mfma_f32_16x16x32_bf16 v[12:15], v[234:237], v[192:195], v[12:15]
	v_mfma_f32_16x16x32_bf16 v[8:11], v[208:211], v[200:203], v[8:11]
	v_mfma_f32_16x16x32_bf16 v[4:7], v[234:237], v[200:203], v[4:7]
	s_add_i32 s48, s48, 2
	s_add_u32 s20, s20, 0x100
	s_addc_u32 s21, s21, 0
	s_add_u32 s3, s3, 0x100
	s_addc_u32 s5, s5, 0
	s_cmp_gt_u32 s48, 61
	s_barrier
	s_cbranch_scc0 .LBB0_1175
	s_lshl_b32 s3, s72, 8
	v_add_u32_e32 v148, s3, v140
	v_lshl_or_b32 v150, s53, 8, v145
	v_ashrrev_i32_e32 v149, 31, v148
	v_cvt_pk_bf16_f32 v128, v128, v129
	v_cvt_pk_bf16_f32 v129, v130, v131
	v_cvt_pk_bf16_f32 v130, v124, v125
	v_add_u32_e32 v124, s3, v142
	v_lshlrev_b64 v[152:153], 11, v[148:149]
	v_ashrrev_i32_e32 v151, 31, v150
	v_ashrrev_i32_e32 v125, 31, v124
	v_cvt_pk_bf16_f32 v120, v120, v121
	v_cvt_pk_bf16_f32 v121, v122, v123
	v_cvt_pk_bf16_f32 v122, v116, v117
	v_add_u32_e32 v116, s3, v143
	v_lshl_add_u64 v[152:153], s[82:83], 0, v[152:153]
	v_lshlrev_b64 v[150:151], 1, v[150:151]
	v_lshlrev_b64 v[124:125], 11, v[124:125]
	v_ashrrev_i32_e32 v117, 31, v116
	v_cvt_pk_bf16_f32 v112, v112, v113
	v_cvt_pk_bf16_f32 v113, v114, v115
	v_cvt_pk_bf16_f32 v114, v108, v109
	v_add_u32_e32 v108, s3, v144
	v_cvt_pk_bf16_f32 v104, v104, v105
	v_cvt_pk_bf16_f32 v105, v106, v107
	v_cvt_pk_bf16_f32 v106, v100, v101
	v_add_u32_e32 v100, 0x80, v148
	v_cvt_pk_bf16_f32 v96, v96, v97
	v_cvt_pk_bf16_f32 v97, v98, v99
	v_cvt_pk_bf16_f32 v98, v92, v93
	v_add_u32_e32 v92, 0x90, v148
	v_cvt_pk_bf16_f32 v88, v88, v89
	v_cvt_pk_bf16_f32 v89, v90, v91
	v_cvt_pk_bf16_f32 v90, v80, v81
	v_add_u32_e32 v80, 0xa0, v148
	v_cvt_pk_bf16_f32 v64, v64, v65
	v_cvt_pk_bf16_f32 v65, v66, v67
	v_cvt_pk_bf16_f32 v66, v60, v61
	v_add_u32_e32 v60, 0xb0, v148
	v_lshl_add_u64 v[152:153], v[152:153], 0, v[150:151]
	v_lshl_add_u64 v[124:125], s[82:83], 0, v[124:125]
	v_lshlrev_b64 v[116:117], 11, v[116:117]
	v_ashrrev_i32_e32 v109, 31, v108
	v_ashrrev_i32_e32 v101, 31, v100
	v_ashrrev_i32_e32 v93, 31, v92
	v_ashrrev_i32_e32 v81, 31, v80
	v_ashrrev_i32_e32 v61, 31, v60
	v_cvt_pk_bf16_f32 v48, v48, v49
	v_cvt_pk_bf16_f32 v49, v50, v51
	v_cvt_pk_bf16_f32 v50, v40, v41
	v_cvt_pk_bf16_f32 v51, v42, v43
	v_cvt_pk_bf16_f32 v40, v84, v85
	v_cvt_pk_bf16_f32 v41, v86, v87
	v_cvt_pk_bf16_f32 v42, v76, v77
	v_cvt_pk_bf16_f32 v43, v78, v79
	v_lshl_add_u64 v[124:125], v[124:125], 0, v[150:151]
	v_lshl_add_u64 v[116:117], s[82:83], 0, v[116:117]
	v_lshlrev_b64 v[108:109], 11, v[108:109]
	v_lshlrev_b64 v[100:101], 11, v[100:101]
	v_lshlrev_b64 v[92:93], 11, v[92:93]
	v_lshlrev_b64 v[80:81], 11, v[80:81]
	v_lshlrev_b64 v[60:61], 11, v[60:61]
	global_store_dwordx4 v[152:153], v[40:43], off offset:256
	v_lshl_add_u64 v[116:117], v[116:117], 0, v[150:151]
	v_lshl_add_u64 v[108:109], s[82:83], 0, v[108:109]
	v_cvt_pk_bf16_f32 v40, v72, v73
	v_cvt_pk_bf16_f32 v41, v74, v75
	v_cvt_pk_bf16_f32 v42, v68, v69
	v_cvt_pk_bf16_f32 v43, v70, v71
	v_lshl_add_u64 v[100:101], s[82:83], 0, v[100:101]
	v_lshl_add_u64 v[92:93], s[82:83], 0, v[92:93]
	v_lshl_add_u64 v[80:81], s[82:83], 0, v[80:81]
	v_lshl_add_u64 v[60:61], s[82:83], 0, v[60:61]
	global_store_dwordx4 v[124:125], v[40:43], off offset:256
	v_cvt_pk_bf16_f32 v131, v126, v127
	v_cvt_pk_bf16_f32 v123, v118, v119
	v_cvt_pk_bf16_f32 v40, v56, v57
	v_cvt_pk_bf16_f32 v41, v58, v59
	v_cvt_pk_bf16_f32 v42, v52, v53
	v_cvt_pk_bf16_f32 v43, v54, v55
	v_cvt_pk_bf16_f32 v115, v110, v111
	v_lshl_add_u64 v[108:109], v[108:109], 0, v[150:151]
	v_cvt_pk_bf16_f32 v107, v102, v103
	v_lshl_add_u64 v[100:101], v[100:101], 0, v[150:151]
	v_cvt_pk_bf16_f32 v99, v94, v95
	v_lshl_add_u64 v[92:93], v[92:93], 0, v[150:151]
	v_cvt_pk_bf16_f32 v91, v82, v83
	v_lshl_add_u64 v[80:81], v[80:81], 0, v[150:151]
	v_cvt_pk_bf16_f32 v67, v62, v63
	v_lshl_add_u64 v[60:61], v[60:61], 0, v[150:151]
	global_store_dwordx4 v[116:117], v[40:43], off offset:256
	v_cvt_pk_bf16_f32 v32, v32, v33
	v_cvt_pk_bf16_f32 v33, v34, v35
	v_cvt_pk_bf16_f32 v40, v44, v45
	v_cvt_pk_bf16_f32 v41, v46, v47
	v_cvt_pk_bf16_f32 v42, v36, v37
	v_cvt_pk_bf16_f32 v43, v38, v39
	v_cvt_pk_bf16_f32 v34, v28, v29
	v_cvt_pk_bf16_f32 v35, v30, v31
	v_cvt_pk_bf16_f32 v24, v24, v25
	v_cvt_pk_bf16_f32 v25, v26, v27
	v_cvt_pk_bf16_f32 v26, v20, v21
	v_cvt_pk_bf16_f32 v27, v22, v23
	v_cvt_pk_bf16_f32 v16, v16, v17
	v_cvt_pk_bf16_f32 v17, v18, v19
	v_cvt_pk_bf16_f32 v18, v12, v13
	v_cvt_pk_bf16_f32 v19, v14, v15
	v_cvt_pk_bf16_f32 v8, v8, v9
	v_cvt_pk_bf16_f32 v9, v10, v11
	v_cvt_pk_bf16_f32 v10, v4, v5
	v_cvt_pk_bf16_f32 v11, v6, v7
	s_and_b64 vcc, exec, s[46:47]
	s_mov_b32 s53, s2
	s_mov_b32 s72, s4
	s_mov_b64 s[16:17], s[10:11]
	s_mov_b64 s[20:21], s[8:9]
	global_store_dwordx4 v[152:153], v[128:131], off
	global_store_dwordx4 v[124:125], v[120:123], off
	global_store_dwordx4 v[116:117], v[112:115], off
	global_store_dwordx4 v[108:109], v[104:107], off
	global_store_dwordx4 v[100:101], v[96:99], off
	global_store_dwordx4 v[92:93], v[88:91], off
	global_store_dwordx4 v[80:81], v[64:67], off
	global_store_dwordx4 v[60:61], v[48:51], off
	global_store_dwordx4 v[108:109], v[40:43], off offset:256
	global_store_dwordx4 v[100:101], v[32:35], off offset:256
	global_store_dwordx4 v[92:93], v[24:27], off offset:256
	global_store_dwordx4 v[80:81], v[16:19], off offset:256
	global_store_dwordx4 v[60:61], v[8:11], off offset:256
	s_cbranch_vccz .LBB0_1166
	s_waitcnt vmcnt(0)
	v_readlane_b32 s72, v255, 28
	s_cmpk_gt_u32 s26, 0xff
	v_readlane_b32 s73, v255, 29
	s_cbranch_scc1 .LBB0_1179
	s_barrier
